# GEMM K-loops: vmcnt and lgkmcnt waits before each pre-MFMA barrier merged into one s_waitcnt, redundant lgkmcnt(0) right after the barrier dropped (8 instructions per K-iteration)
# baseline (speedup 1.0000x reference)
.LBB0_342:
	s_and_b64 s[10:11], s[48:49], exec
	s_cselect_b32 s50, s45, s5
	s_cselect_b32 s51, s44, s4
	s_cselect_b32 s53, s47, s9
	s_cselect_b32 s54, s46, s8
	s_add_u32 s55, s8, 0x100
	s_addc_u32 s78, s9, 0
	s_add_u32 s4, s4, 0x40080
	v_mov_b32_e32 v0, 0
	s_addc_u32 s5, s5, 0
	s_mov_b32 s79, -2
	ds_read_b128 v[128:131], v169
	ds_read_b128 v[132:135], v169 offset:1024
	ds_read_b128 v[136:139], v169 offset:2048
	ds_read_b128 v[140:143], v169 offset:3072
	ds_read_b128 v[158:161], v170
	ds_read_b128 v[162:165], v170 offset:1024
	ds_read_b128 v[178:181], v170 offset:2048
	ds_read_b128 v[182:185], v170 offset:3072
	s_add_u32 s8, s4, 0xfffc0080
	s_addc_u32 s9, s5, -1
	s_cmp_eq_u32 s79, 12
	s_cselect_b32 s11, s50, s9
	s_cselect_b32 s10, s51, s8
	s_cselect_b32 s9, s53, s78
	s_cselect_b32 s8, s54, s55
	v_lshl_add_u64 v[218:219], s[4:5], 0, v[156:157]
	s_add_i32 m0, s28, 0xc000
	ds_read_b128 v[186:189], v171
	ds_read_b128 v[190:193], v171 offset:1024
	ds_read_b128 v[194:197], v171 offset:2048
	ds_read_b128 v[198:201], v171 offset:3072
	ds_read_b128 v[202:205], v171 offset:4096
	ds_read_b128 v[206:209], v171 offset:5120
	ds_read_b128 v[210:213], v171 offset:6144
	ds_read_b128 v[214:217], v171 offset:7168
	global_load_lds_dwordx4 v[218:219], off
	v_lshl_add_u64 v[218:219], s[4:5], 0, v[154:155]
	s_add_i32 m0, s28, 0xe000
	s_nop 0
	global_load_lds_dwordx4 v[218:219], off
	s_waitcnt vmcnt(8) lgkmcnt(0)
	s_barrier
	v_mfma_f32_16x16x32_bf16 v[124:127], v[128:131], v[186:189], 0
	v_mfma_f32_16x16x32_bf16 v[120:123], v[136:139], v[186:189], 0
	v_mfma_f32_16x16x32_bf16 v[108:111], v[128:131], v[194:197], 0
	v_mfma_f32_16x16x32_bf16 v[104:107], v[136:139], v[194:197], 0
	v_mfma_f32_16x16x32_bf16 v[92:95], v[128:131], v[202:205], 0
	v_mfma_f32_16x16x32_bf16 v[88:91], v[136:139], v[202:205], 0
	v_mfma_f32_16x16x32_bf16 v[76:79], v[128:131], v[210:213], 0
	v_mfma_f32_16x16x32_bf16 v[72:75], v[136:139], v[210:213], 0
	v_mfma_f32_16x16x32_bf16 v[124:127], v[132:135], v[190:193], v[124:127]
	v_mfma_f32_16x16x32_bf16 v[120:123], v[140:143], v[190:193], v[120:123]
	v_mfma_f32_16x16x32_bf16 v[108:111], v[132:135], v[198:201], v[108:111]
	v_mfma_f32_16x16x32_bf16 v[104:107], v[140:143], v[198:201], v[104:107]
	v_mfma_f32_16x16x32_bf16 v[92:95], v[132:135], v[206:209], v[92:95]
	v_mfma_f32_16x16x32_bf16 v[88:91], v[140:143], v[206:209], v[88:91]
	v_mfma_f32_16x16x32_bf16 v[76:79], v[132:135], v[214:217], v[76:79]
	v_mfma_f32_16x16x32_bf16 v[72:75], v[140:143], v[214:217], v[72:75]
	v_mfma_f32_16x16x32_bf16 v[116:119], v[158:161], v[186:189], 0
	v_mfma_f32_16x16x32_bf16 v[112:115], v[178:181], v[186:189], 0
	v_mfma_f32_16x16x32_bf16 v[100:103], v[158:161], v[194:197], 0
	v_mfma_f32_16x16x32_bf16 v[96:99], v[178:181], v[194:197], 0
	v_mfma_f32_16x16x32_bf16 v[84:87], v[158:161], v[202:205], 0
	v_mfma_f32_16x16x32_bf16 v[80:83], v[178:181], v[202:205], 0
	v_mfma_f32_16x16x32_bf16 v[68:71], v[158:161], v[210:213], 0
	v_mfma_f32_16x16x32_bf16 v[64:67], v[178:181], v[210:213], 0
	v_mfma_f32_16x16x32_bf16 v[116:119], v[162:165], v[190:193], v[116:119]
	v_mfma_f32_16x16x32_bf16 v[112:115], v[182:185], v[190:193], v[112:115]
	v_mfma_f32_16x16x32_bf16 v[100:103], v[162:165], v[198:201], v[100:103]
	v_mfma_f32_16x16x32_bf16 v[96:99], v[182:185], v[198:201], v[96:99]
	v_mfma_f32_16x16x32_bf16 v[84:87], v[162:165], v[206:209], v[84:87]
	v_mfma_f32_16x16x32_bf16 v[80:83], v[182:185], v[206:209], v[80:83]
	v_mfma_f32_16x16x32_bf16 v[68:71], v[162:165], v[214:217], v[68:71]
	v_mfma_f32_16x16x32_bf16 v[64:67], v[182:185], v[214:217], v[64:67]
	s_barrier
	s_add_i32 s26, s63, s13
	v_lshl_add_u64 v[218:219], s[8:9], 0, v[146:147]
	s_mov_b32 m0, s26
	ds_read_b128 v[186:189], v171 offset:16384
	ds_read_b128 v[190:193], v171 offset:17408
	ds_read_b128 v[194:197], v171 offset:18432
	ds_read_b128 v[198:201], v171 offset:19456
	ds_read_b128 v[202:205], v171 offset:20480
	ds_read_b128 v[206:209], v171 offset:21504
	ds_read_b128 v[210:213], v171 offset:22528
	ds_read_b128 v[214:217], v171 offset:23552
	global_load_lds_dwordx4 v[218:219], off
	s_add_i32 m0, s26, 0x2000
	s_add_u32 s26, s8, 0x40000
	v_lshl_add_u64 v[220:221], s[8:9], 0, v[150:151]
	s_addc_u32 s27, s9, 0
	s_add_i32 s77, s64, s13
	global_load_lds_dwordx4 v[220:221], off
	v_lshl_add_u64 v[222:223], s[26:27], 0, v[146:147]
	s_mov_b32 m0, s77
	v_lshl_add_u64 v[224:225], s[10:11], 0, v[148:149]
	global_load_lds_dwordx4 v[222:223], off
	v_lshl_add_u64 v[222:223], s[26:27], 0, v[150:151]
	s_add_i32 m0, s77, 0x2000
	s_nop 0
	global_load_lds_dwordx4 v[222:223], off
	v_lshl_add_u64 v[222:223], s[10:11], 0, v[144:145]
	s_mov_b32 m0, s28
	s_nop 0
	global_load_lds_dwordx4 v[222:223], off
	s_mov_b32 m0, s29
	s_nop 0
	global_load_lds_dwordx4 v[224:225], off
	s_waitcnt vmcnt(8) lgkmcnt(0)
	s_barrier
	v_mfma_f32_16x16x32_bf16 v[60:63], v[128:131], v[186:189], 0
	v_mfma_f32_16x16x32_bf16 v[56:59], v[136:139], v[186:189], 0
	v_mfma_f32_16x16x32_bf16 v[44:47], v[128:131], v[194:197], 0
	v_mfma_f32_16x16x32_bf16 v[40:43], v[136:139], v[194:197], 0
	v_mfma_f32_16x16x32_bf16 v[28:31], v[128:131], v[202:205], 0
	v_mfma_f32_16x16x32_bf16 v[24:27], v[136:139], v[202:205], 0
	v_mfma_f32_16x16x32_bf16 v[12:15], v[128:131], v[210:213], 0
	v_mfma_f32_16x16x32_bf16 v[8:11], v[136:139], v[210:213], 0
	v_mfma_f32_16x16x32_bf16 v[60:63], v[132:135], v[190:193], v[60:63]
	v_mfma_f32_16x16x32_bf16 v[56:59], v[140:143], v[190:193], v[56:59]
	v_mfma_f32_16x16x32_bf16 v[44:47], v[132:135], v[198:201], v[44:47]
	v_mfma_f32_16x16x32_bf16 v[40:43], v[140:143], v[198:201], v[40:43]
	v_mfma_f32_16x16x32_bf16 v[28:31], v[132:135], v[206:209], v[28:31]
	v_mfma_f32_16x16x32_bf16 v[24:27], v[140:143], v[206:209], v[24:27]
	v_mfma_f32_16x16x32_bf16 v[12:15], v[132:135], v[214:217], v[12:15]
	v_mfma_f32_16x16x32_bf16 v[8:11], v[140:143], v[214:217], v[8:11]
	v_mfma_f32_16x16x32_bf16 v[52:55], v[158:161], v[186:189], 0
	v_mfma_f32_16x16x32_bf16 v[48:51], v[178:181], v[186:189], 0
	v_mfma_f32_16x16x32_bf16 v[36:39], v[158:161], v[194:197], 0
	v_mfma_f32_16x16x32_bf16 v[32:35], v[178:181], v[194:197], 0
	v_mfma_f32_16x16x32_bf16 v[20:23], v[158:161], v[202:205], 0
	v_mfma_f32_16x16x32_bf16 v[16:19], v[178:181], v[202:205], 0
	v_mfma_f32_16x16x32_bf16 v[4:7], v[158:161], v[210:213], 0
	v_mfma_f32_16x16x32_bf16 v[0:3], v[178:181], v[210:213], 0
	v_mfma_f32_16x16x32_bf16 v[52:55], v[162:165], v[190:193], v[52:55]
	v_mfma_f32_16x16x32_bf16 v[48:51], v[182:185], v[190:193], v[48:51]
	v_mfma_f32_16x16x32_bf16 v[36:39], v[162:165], v[198:201], v[36:39]
	v_mfma_f32_16x16x32_bf16 v[32:35], v[182:185], v[198:201], v[32:35]
	v_mfma_f32_16x16x32_bf16 v[20:23], v[162:165], v[206:209], v[20:23]
	v_mfma_f32_16x16x32_bf16 v[16:19], v[182:185], v[206:209], v[16:19]
	v_mfma_f32_16x16x32_bf16 v[4:7], v[162:165], v[214:217], v[4:7]
	v_mfma_f32_16x16x32_bf16 v[0:3], v[182:185], v[214:217], v[0:3]
	s_barrier
	s_add_i32 s26, 0, 0x18000
	s_add_i32 s27, 0, 0x1c000
	v_add_u32_e32 v140, s26, v168
	v_add_u32_e32 v152, s27, v168
	ds_read_b128 v[128:131], v140
	ds_read_b128 v[132:135], v140 offset:1024
	ds_read_b128 v[136:139], v140 offset:2048
	ds_read_b128 v[140:143], v140 offset:3072
	ds_read_b128 v[158:161], v152
	ds_read_b128 v[162:165], v152 offset:1024
	ds_read_b128 v[178:181], v152 offset:2048
	ds_read_b128 v[182:185], v152 offset:3072
	s_add_u32 s10, s10, 0x40000
	s_addc_u32 s11, s11, 0
	s_mov_b32 m0, s56
	v_lshl_add_u64 v[226:227], s[10:11], 0, v[144:145]
	ds_read_b128 v[186:189], v171 offset:32768
	ds_read_b128 v[190:193], v171 offset:33792
	ds_read_b128 v[194:197], v171 offset:34816
	ds_read_b128 v[198:201], v171 offset:35840
	ds_read_b128 v[202:205], v171 offset:36864
	ds_read_b128 v[206:209], v171 offset:37888
	ds_read_b128 v[210:213], v171 offset:38912
	ds_read_b128 v[214:217], v171 offset:39936
	global_load_lds_dwordx4 v[226:227], off
	v_lshl_add_u64 v[226:227], s[10:11], 0, v[148:149]
	s_mov_b32 m0, s57
	s_nop 0
	global_load_lds_dwordx4 v[226:227], off
	s_waitcnt vmcnt(8) lgkmcnt(0)
	s_barrier
	v_mfma_f32_16x16x32_bf16 v[124:127], v[128:131], v[186:189], v[124:127]
	v_mfma_f32_16x16x32_bf16 v[120:123], v[136:139], v[186:189], v[120:123]
	v_mfma_f32_16x16x32_bf16 v[108:111], v[128:131], v[194:197], v[108:111]
	v_mfma_f32_16x16x32_bf16 v[104:107], v[136:139], v[194:197], v[104:107]
	v_mfma_f32_16x16x32_bf16 v[92:95], v[128:131], v[202:205], v[92:95]
	v_mfma_f32_16x16x32_bf16 v[88:91], v[136:139], v[202:205], v[88:91]
	v_mfma_f32_16x16x32_bf16 v[76:79], v[128:131], v[210:213], v[76:79]
	v_mfma_f32_16x16x32_bf16 v[72:75], v[136:139], v[210:213], v[72:75]
	v_mfma_f32_16x16x32_bf16 v[124:127], v[132:135], v[190:193], v[124:127]
	v_mfma_f32_16x16x32_bf16 v[120:123], v[140:143], v[190:193], v[120:123]
	v_mfma_f32_16x16x32_bf16 v[108:111], v[132:135], v[198:201], v[108:111]
	v_mfma_f32_16x16x32_bf16 v[104:107], v[140:143], v[198:201], v[104:107]
	v_mfma_f32_16x16x32_bf16 v[92:95], v[132:135], v[206:209], v[92:95]
	v_mfma_f32_16x16x32_bf16 v[88:91], v[140:143], v[206:209], v[88:91]
	v_mfma_f32_16x16x32_bf16 v[76:79], v[132:135], v[214:217], v[76:79]
	v_mfma_f32_16x16x32_bf16 v[72:75], v[140:143], v[214:217], v[72:75]
	v_mfma_f32_16x16x32_bf16 v[116:119], v[158:161], v[186:189], v[116:119]
	v_mfma_f32_16x16x32_bf16 v[112:115], v[178:181], v[186:189], v[112:115]
	v_mfma_f32_16x16x32_bf16 v[100:103], v[158:161], v[194:197], v[100:103]
	v_mfma_f32_16x16x32_bf16 v[96:99], v[178:181], v[194:197], v[96:99]
	v_mfma_f32_16x16x32_bf16 v[84:87], v[158:161], v[202:205], v[84:87]
	v_mfma_f32_16x16x32_bf16 v[80:83], v[178:181], v[202:205], v[80:83]
	v_mfma_f32_16x16x32_bf16 v[68:71], v[158:161], v[210:213], v[68:71]
	v_mfma_f32_16x16x32_bf16 v[64:67], v[178:181], v[210:213], v[64:67]
	v_mfma_f32_16x16x32_bf16 v[116:119], v[162:165], v[190:193], v[116:119]
	v_mfma_f32_16x16x32_bf16 v[112:115], v[182:185], v[190:193], v[112:115]
	v_mfma_f32_16x16x32_bf16 v[100:103], v[162:165], v[198:201], v[100:103]
	v_mfma_f32_16x16x32_bf16 v[96:99], v[182:185], v[198:201], v[96:99]
	v_mfma_f32_16x16x32_bf16 v[84:87], v[162:165], v[206:209], v[84:87]
	v_mfma_f32_16x16x32_bf16 v[80:83], v[182:185], v[206:209], v[80:83]
	v_mfma_f32_16x16x32_bf16 v[68:71], v[162:165], v[214:217], v[68:71]
	v_mfma_f32_16x16x32_bf16 v[64:67], v[182:185], v[214:217], v[64:67]
	s_barrier
	s_add_i32 s10, s26, s13
	v_lshl_add_u64 v[218:219], v[218:219], 0, s[34:35]
	s_mov_b32 m0, s10
	ds_read_b128 v[186:189], v171 offset:49152
	ds_read_b128 v[190:193], v171 offset:50176
	ds_read_b128 v[194:197], v171 offset:51200
	ds_read_b128 v[198:201], v171 offset:52224
	ds_read_b128 v[202:205], v171 offset:53248
	ds_read_b128 v[206:209], v171 offset:54272
	ds_read_b128 v[210:213], v171 offset:55296
	ds_read_b128 v[214:217], v171 offset:56320
	global_load_lds_dwordx4 v[218:219], off
	s_add_i32 m0, s10, 0x2000
	s_add_u32 s8, s8, 0x40080
	v_lshl_add_u64 v[218:219], v[220:221], 0, s[34:35]
	s_addc_u32 s9, s9, 0
	s_add_i32 s10, s27, s13
	global_load_lds_dwordx4 v[218:219], off
	v_lshl_add_u64 v[218:219], s[8:9], 0, v[146:147]
	s_mov_b32 m0, s10
	s_nop 0
	global_load_lds_dwordx4 v[218:219], off
	v_lshl_add_u64 v[218:219], s[8:9], 0, v[150:151]
	s_add_i32 m0, s10, 0x2000
	s_nop 0
	global_load_lds_dwordx4 v[218:219], off
	v_lshl_add_u64 v[218:219], v[222:223], 0, s[34:35]
	s_mov_b32 m0, s61
	s_nop 0
	global_load_lds_dwordx4 v[218:219], off
	v_lshl_add_u64 v[218:219], v[224:225], 0, s[34:35]
	s_mov_b32 m0, s62
	s_nop 0
	global_load_lds_dwordx4 v[218:219], off
	s_waitcnt vmcnt(8) lgkmcnt(0)
	s_barrier
	v_mfma_f32_16x16x32_bf16 v[60:63], v[128:131], v[186:189], v[60:63]
	v_mfma_f32_16x16x32_bf16 v[56:59], v[136:139], v[186:189], v[56:59]
	v_mfma_f32_16x16x32_bf16 v[44:47], v[128:131], v[194:197], v[44:47]
	v_mfma_f32_16x16x32_bf16 v[40:43], v[136:139], v[194:197], v[40:43]
	v_mfma_f32_16x16x32_bf16 v[28:31], v[128:131], v[202:205], v[28:31]
	v_mfma_f32_16x16x32_bf16 v[24:27], v[136:139], v[202:205], v[24:27]
	v_mfma_f32_16x16x32_bf16 v[12:15], v[128:131], v[210:213], v[12:15]
	v_mfma_f32_16x16x32_bf16 v[8:11], v[136:139], v[210:213], v[8:11]
	v_mfma_f32_16x16x32_bf16 v[60:63], v[132:135], v[190:193], v[60:63]
	v_mfma_f32_16x16x32_bf16 v[56:59], v[140:143], v[190:193], v[56:59]
	v_mfma_f32_16x16x32_bf16 v[44:47], v[132:135], v[198:201], v[44:47]
	v_mfma_f32_16x16x32_bf16 v[40:43], v[140:143], v[198:201], v[40:43]
	v_mfma_f32_16x16x32_bf16 v[28:31], v[132:135], v[206:209], v[28:31]
	v_mfma_f32_16x16x32_bf16 v[24:27], v[140:143], v[206:209], v[24:27]
	v_mfma_f32_16x16x32_bf16 v[12:15], v[132:135], v[214:217], v[12:15]
	v_mfma_f32_16x16x32_bf16 v[8:11], v[140:143], v[214:217], v[8:11]
	v_mfma_f32_16x16x32_bf16 v[52:55], v[158:161], v[186:189], v[52:55]
	v_mfma_f32_16x16x32_bf16 v[48:51], v[178:181], v[186:189], v[48:51]
	v_mfma_f32_16x16x32_bf16 v[36:39], v[158:161], v[194:197], v[36:39]
	v_mfma_f32_16x16x32_bf16 v[32:35], v[178:181], v[194:197], v[32:35]
	v_mfma_f32_16x16x32_bf16 v[20:23], v[158:161], v[202:205], v[20:23]
	v_mfma_f32_16x16x32_bf16 v[16:19], v[178:181], v[202:205], v[16:19]
	v_mfma_f32_16x16x32_bf16 v[4:7], v[158:161], v[210:213], v[4:7]
	v_mfma_f32_16x16x32_bf16 v[0:3], v[178:181], v[210:213], v[0:3]
	v_mfma_f32_16x16x32_bf16 v[52:55], v[162:165], v[190:193], v[52:55]
	v_mfma_f32_16x16x32_bf16 v[48:51], v[182:185], v[190:193], v[48:51]
	v_mfma_f32_16x16x32_bf16 v[36:39], v[162:165], v[198:201], v[36:39]
	v_mfma_f32_16x16x32_bf16 v[32:35], v[182:185], v[198:201], v[32:35]
	v_mfma_f32_16x16x32_bf16 v[20:23], v[162:165], v[206:209], v[20:23]
	v_mfma_f32_16x16x32_bf16 v[16:19], v[182:185], v[206:209], v[16:19]
	v_mfma_f32_16x16x32_bf16 v[4:7], v[162:165], v[214:217], v[4:7]
	v_mfma_f32_16x16x32_bf16 v[0:3], v[182:185], v[214:217], v[0:3]
	s_barrier
	s_add_i32 s79, s79, 2
	s_add_u32 s55, s55, 0x100
	s_addc_u32 s78, s78, 0
	s_add_u32 s4, s4, 0x100
	s_addc_u32 s5, s5, 0
.LBB0_343:
	ds_read_b128 v[128:131], v169
	ds_read_b128 v[132:135], v169 offset:1024
	ds_read_b128 v[136:139], v169 offset:2048
	ds_read_b128 v[140:143], v169 offset:3072
	ds_read_b128 v[158:161], v170
	ds_read_b128 v[162:165], v170 offset:1024
	ds_read_b128 v[178:181], v170 offset:2048
	ds_read_b128 v[182:185], v170 offset:3072
	s_add_u32 s8, s4, 0xfffc0080
	s_addc_u32 s9, s5, -1
	s_cmp_eq_u32 s79, 12
	s_cselect_b32 s11, s50, s9
	s_cselect_b32 s10, s51, s8
	s_cselect_b32 s9, s53, s78
	s_cselect_b32 s8, s54, s55
	v_lshl_add_u64 v[218:219], s[4:5], 0, v[156:157]
	s_add_i32 m0, s28, 0xc000
	ds_read_b128 v[186:189], v171
	ds_read_b128 v[190:193], v171 offset:1024
	ds_read_b128 v[194:197], v171 offset:2048
	ds_read_b128 v[198:201], v171 offset:3072
	ds_read_b128 v[202:205], v171 offset:4096
	ds_read_b128 v[206:209], v171 offset:5120
	ds_read_b128 v[210:213], v171 offset:6144
	ds_read_b128 v[214:217], v171 offset:7168
	global_load_lds_dwordx4 v[218:219], off
	v_lshl_add_u64 v[218:219], s[4:5], 0, v[154:155]
	s_add_i32 m0, s28, 0xe000
	s_nop 0
	global_load_lds_dwordx4 v[218:219], off
	s_waitcnt vmcnt(8) lgkmcnt(0)
	s_barrier
	v_mfma_f32_16x16x32_bf16 v[124:127], v[128:131], v[186:189], v[124:127]
	v_mfma_f32_16x16x32_bf16 v[120:123], v[136:139], v[186:189], v[120:123]
	v_mfma_f32_16x16x32_bf16 v[108:111], v[128:131], v[194:197], v[108:111]
	v_mfma_f32_16x16x32_bf16 v[104:107], v[136:139], v[194:197], v[104:107]
	v_mfma_f32_16x16x32_bf16 v[92:95], v[128:131], v[202:205], v[92:95]
	v_mfma_f32_16x16x32_bf16 v[88:91], v[136:139], v[202:205], v[88:91]
	v_mfma_f32_16x16x32_bf16 v[76:79], v[128:131], v[210:213], v[76:79]
	v_mfma_f32_16x16x32_bf16 v[72:75], v[136:139], v[210:213], v[72:75]
	v_mfma_f32_16x16x32_bf16 v[124:127], v[132:135], v[190:193], v[124:127]
	v_mfma_f32_16x16x32_bf16 v[120:123], v[140:143], v[190:193], v[120:123]
	v_mfma_f32_16x16x32_bf16 v[108:111], v[132:135], v[198:201], v[108:111]
	v_mfma_f32_16x16x32_bf16 v[104:107], v[140:143], v[198:201], v[104:107]
	v_mfma_f32_16x16x32_bf16 v[92:95], v[132:135], v[206:209], v[92:95]
	v_mfma_f32_16x16x32_bf16 v[88:91], v[140:143], v[206:209], v[88:91]
	v_mfma_f32_16x16x32_bf16 v[76:79], v[132:135], v[214:217], v[76:79]
	v_mfma_f32_16x16x32_bf16 v[72:75], v[140:143], v[214:217], v[72:75]
	v_mfma_f32_16x16x32_bf16 v[116:119], v[158:161], v[186:189], v[116:119]
	v_mfma_f32_16x16x32_bf16 v[112:115], v[178:181], v[186:189], v[112:115]
	v_mfma_f32_16x16x32_bf16 v[100:103], v[158:161], v[194:197], v[100:103]
	v_mfma_f32_16x16x32_bf16 v[96:99], v[178:181], v[194:197], v[96:99]
	v_mfma_f32_16x16x32_bf16 v[84:87], v[158:161], v[202:205], v[84:87]
	v_mfma_f32_16x16x32_bf16 v[80:83], v[178:181], v[202:205], v[80:83]
	v_mfma_f32_16x16x32_bf16 v[68:71], v[158:161], v[210:213], v[68:71]
	v_mfma_f32_16x16x32_bf16 v[64:67], v[178:181], v[210:213], v[64:67]
	v_mfma_f32_16x16x32_bf16 v[116:119], v[162:165], v[190:193], v[116:119]
	v_mfma_f32_16x16x32_bf16 v[112:115], v[182:185], v[190:193], v[112:115]
	v_mfma_f32_16x16x32_bf16 v[100:103], v[162:165], v[198:201], v[100:103]
	v_mfma_f32_16x16x32_bf16 v[96:99], v[182:185], v[198:201], v[96:99]
	v_mfma_f32_16x16x32_bf16 v[84:87], v[162:165], v[206:209], v[84:87]
	v_mfma_f32_16x16x32_bf16 v[80:83], v[182:185], v[206:209], v[80:83]
	v_mfma_f32_16x16x32_bf16 v[68:71], v[162:165], v[214:217], v[68:71]
	v_mfma_f32_16x16x32_bf16 v[64:67], v[182:185], v[214:217], v[64:67]
	s_barrier
	s_add_i32 s26, s63, s13
	v_lshl_add_u64 v[218:219], s[8:9], 0, v[146:147]
	s_mov_b32 m0, s26
	ds_read_b128 v[186:189], v171 offset:16384
	ds_read_b128 v[190:193], v171 offset:17408
	ds_read_b128 v[194:197], v171 offset:18432
	ds_read_b128 v[198:201], v171 offset:19456
	ds_read_b128 v[202:205], v171 offset:20480
	ds_read_b128 v[206:209], v171 offset:21504
	ds_read_b128 v[210:213], v171 offset:22528
	ds_read_b128 v[214:217], v171 offset:23552
	global_load_lds_dwordx4 v[218:219], off
	s_add_i32 m0, s26, 0x2000
	s_add_u32 s26, s8, 0x40000
	v_lshl_add_u64 v[220:221], s[8:9], 0, v[150:151]
	s_addc_u32 s27, s9, 0
	s_add_i32 s77, s64, s13
	global_load_lds_dwordx4 v[220:221], off
	v_lshl_add_u64 v[222:223], s[26:27], 0, v[146:147]
	s_mov_b32 m0, s77
	v_lshl_add_u64 v[224:225], s[10:11], 0, v[148:149]
	global_load_lds_dwordx4 v[222:223], off
	v_lshl_add_u64 v[222:223], s[26:27], 0, v[150:151]
	s_add_i32 m0, s77, 0x2000
	s_nop 0
	global_load_lds_dwordx4 v[222:223], off
	v_lshl_add_u64 v[222:223], s[10:11], 0, v[144:145]
	s_mov_b32 m0, s28
	s_nop 0
	global_load_lds_dwordx4 v[222:223], off
	s_mov_b32 m0, s29
	s_nop 0
	global_load_lds_dwordx4 v[224:225], off
	s_waitcnt vmcnt(8) lgkmcnt(0)
	s_barrier
	v_mfma_f32_16x16x32_bf16 v[60:63], v[128:131], v[186:189], v[60:63]
	v_mfma_f32_16x16x32_bf16 v[56:59], v[136:139], v[186:189], v[56:59]
	v_mfma_f32_16x16x32_bf16 v[44:47], v[128:131], v[194:197], v[44:47]
	v_mfma_f32_16x16x32_bf16 v[40:43], v[136:139], v[194:197], v[40:43]
	v_mfma_f32_16x16x32_bf16 v[28:31], v[128:131], v[202:205], v[28:31]
	v_mfma_f32_16x16x32_bf16 v[24:27], v[136:139], v[202:205], v[24:27]
	v_mfma_f32_16x16x32_bf16 v[12:15], v[128:131], v[210:213], v[12:15]
	v_mfma_f32_16x16x32_bf16 v[8:11], v[136:139], v[210:213], v[8:11]
	v_mfma_f32_16x16x32_bf16 v[60:63], v[132:135], v[190:193], v[60:63]
	v_mfma_f32_16x16x32_bf16 v[56:59], v[140:143], v[190:193], v[56:59]
	v_mfma_f32_16x16x32_bf16 v[44:47], v[132:135], v[198:201], v[44:47]
	v_mfma_f32_16x16x32_bf16 v[40:43], v[140:143], v[198:201], v[40:43]
	v_mfma_f32_16x16x32_bf16 v[28:31], v[132:135], v[206:209], v[28:31]
	v_mfma_f32_16x16x32_bf16 v[24:27], v[140:143], v[206:209], v[24:27]
	v_mfma_f32_16x16x32_bf16 v[12:15], v[132:135], v[214:217], v[12:15]
	v_mfma_f32_16x16x32_bf16 v[8:11], v[140:143], v[214:217], v[8:11]
	v_mfma_f32_16x16x32_bf16 v[52:55], v[158:161], v[186:189], v[52:55]
	v_mfma_f32_16x16x32_bf16 v[48:51], v[178:181], v[186:189], v[48:51]
	v_mfma_f32_16x16x32_bf16 v[36:39], v[158:161], v[194:197], v[36:39]
	v_mfma_f32_16x16x32_bf16 v[32:35], v[178:181], v[194:197], v[32:35]
	v_mfma_f32_16x16x32_bf16 v[20:23], v[158:161], v[202:205], v[20:23]
	v_mfma_f32_16x16x32_bf16 v[16:19], v[178:181], v[202:205], v[16:19]
	v_mfma_f32_16x16x32_bf16 v[4:7], v[158:161], v[210:213], v[4:7]
	v_mfma_f32_16x16x32_bf16 v[0:3], v[178:181], v[210:213], v[0:3]
	v_mfma_f32_16x16x32_bf16 v[52:55], v[162:165], v[190:193], v[52:55]
	v_mfma_f32_16x16x32_bf16 v[48:51], v[182:185], v[190:193], v[48:51]
	v_mfma_f32_16x16x32_bf16 v[36:39], v[162:165], v[198:201], v[36:39]
	v_mfma_f32_16x16x32_bf16 v[32:35], v[182:185], v[198:201], v[32:35]
	v_mfma_f32_16x16x32_bf16 v[20:23], v[162:165], v[206:209], v[20:23]
	v_mfma_f32_16x16x32_bf16 v[16:19], v[182:185], v[206:209], v[16:19]
	v_mfma_f32_16x16x32_bf16 v[4:7], v[162:165], v[214:217], v[4:7]
	v_mfma_f32_16x16x32_bf16 v[0:3], v[182:185], v[214:217], v[0:3]
	s_barrier
	s_add_i32 s26, 0, 0x18000
	s_add_i32 s27, 0, 0x1c000
	v_add_u32_e32 v140, s26, v168
	v_add_u32_e32 v152, s27, v168
	ds_read_b128 v[128:131], v140
	ds_read_b128 v[132:135], v140 offset:1024
	ds_read_b128 v[136:139], v140 offset:2048
	ds_read_b128 v[140:143], v140 offset:3072
	ds_read_b128 v[158:161], v152
	ds_read_b128 v[162:165], v152 offset:1024
	ds_read_b128 v[178:181], v152 offset:2048
	ds_read_b128 v[182:185], v152 offset:3072
	s_add_u32 s10, s10, 0x40000
	s_addc_u32 s11, s11, 0
	s_mov_b32 m0, s56
	v_lshl_add_u64 v[226:227], s[10:11], 0, v[144:145]
	ds_read_b128 v[186:189], v171 offset:32768
	ds_read_b128 v[190:193], v171 offset:33792
	ds_read_b128 v[194:197], v171 offset:34816
	ds_read_b128 v[198:201], v171 offset:35840
	ds_read_b128 v[202:205], v171 offset:36864
	ds_read_b128 v[206:209], v171 offset:37888
	ds_read_b128 v[210:213], v171 offset:38912
	ds_read_b128 v[214:217], v171 offset:39936
	global_load_lds_dwordx4 v[226:227], off
	v_lshl_add_u64 v[226:227], s[10:11], 0, v[148:149]
	s_mov_b32 m0, s57
	s_nop 0
	global_load_lds_dwordx4 v[226:227], off
	s_waitcnt vmcnt(8) lgkmcnt(0)
	s_barrier
	v_mfma_f32_16x16x32_bf16 v[124:127], v[128:131], v[186:189], v[124:127]
	v_mfma_f32_16x16x32_bf16 v[120:123], v[136:139], v[186:189], v[120:123]
	v_mfma_f32_16x16x32_bf16 v[108:111], v[128:131], v[194:197], v[108:111]
	v_mfma_f32_16x16x32_bf16 v[104:107], v[136:139], v[194:197], v[104:107]
	v_mfma_f32_16x16x32_bf16 v[92:95], v[128:131], v[202:205], v[92:95]
	v_mfma_f32_16x16x32_bf16 v[88:91], v[136:139], v[202:205], v[88:91]
	v_mfma_f32_16x16x32_bf16 v[76:79], v[128:131], v[210:213], v[76:79]
	v_mfma_f32_16x16x32_bf16 v[72:75], v[136:139], v[210:213], v[72:75]
	v_mfma_f32_16x16x32_bf16 v[124:127], v[132:135], v[190:193], v[124:127]
	v_mfma_f32_16x16x32_bf16 v[120:123], v[140:143], v[190:193], v[120:123]
	v_mfma_f32_16x16x32_bf16 v[108:111], v[132:135], v[198:201], v[108:111]
	v_mfma_f32_16x16x32_bf16 v[104:107], v[140:143], v[198:201], v[104:107]
	v_mfma_f32_16x16x32_bf16 v[92:95], v[132:135], v[206:209], v[92:95]
	v_mfma_f32_16x16x32_bf16 v[88:91], v[140:143], v[206:209], v[88:91]
	v_mfma_f32_16x16x32_bf16 v[76:79], v[132:135], v[214:217], v[76:79]
	v_mfma_f32_16x16x32_bf16 v[72:75], v[140:143], v[214:217], v[72:75]
	v_mfma_f32_16x16x32_bf16 v[116:119], v[158:161], v[186:189], v[116:119]
	v_mfma_f32_16x16x32_bf16 v[112:115], v[178:181], v[186:189], v[112:115]
	v_mfma_f32_16x16x32_bf16 v[100:103], v[158:161], v[194:197], v[100:103]
	v_mfma_f32_16x16x32_bf16 v[96:99], v[178:181], v[194:197], v[96:99]
	v_mfma_f32_16x16x32_bf16 v[84:87], v[158:161], v[202:205], v[84:87]
	v_mfma_f32_16x16x32_bf16 v[80:83], v[178:181], v[202:205], v[80:83]
	v_mfma_f32_16x16x32_bf16 v[68:71], v[158:161], v[210:213], v[68:71]
	v_mfma_f32_16x16x32_bf16 v[64:67], v[178:181], v[210:213], v[64:67]
	v_mfma_f32_16x16x32_bf16 v[116:119], v[162:165], v[190:193], v[116:119]
	v_mfma_f32_16x16x32_bf16 v[112:115], v[182:185], v[190:193], v[112:115]
	v_mfma_f32_16x16x32_bf16 v[100:103], v[162:165], v[198:201], v[100:103]
	v_mfma_f32_16x16x32_bf16 v[96:99], v[182:185], v[198:201], v[96:99]
	v_mfma_f32_16x16x32_bf16 v[84:87], v[162:165], v[206:209], v[84:87]
	v_mfma_f32_16x16x32_bf16 v[80:83], v[182:185], v[206:209], v[80:83]
	v_mfma_f32_16x16x32_bf16 v[68:71], v[162:165], v[214:217], v[68:71]
	v_mfma_f32_16x16x32_bf16 v[64:67], v[182:185], v[214:217], v[64:67]
	s_barrier
	s_add_i32 s10, s26, s13
	v_lshl_add_u64 v[218:219], v[218:219], 0, s[34:35]
	s_mov_b32 m0, s10
	ds_read_b128 v[186:189], v171 offset:49152
	ds_read_b128 v[190:193], v171 offset:50176
	ds_read_b128 v[194:197], v171 offset:51200
	ds_read_b128 v[198:201], v171 offset:52224
	ds_read_b128 v[202:205], v171 offset:53248
	ds_read_b128 v[206:209], v171 offset:54272
	ds_read_b128 v[210:213], v171 offset:55296
	ds_read_b128 v[214:217], v171 offset:56320
	global_load_lds_dwordx4 v[218:219], off
	s_add_i32 m0, s10, 0x2000
	s_add_u32 s8, s8, 0x40080
	v_lshl_add_u64 v[218:219], v[220:221], 0, s[34:35]
	s_addc_u32 s9, s9, 0
	s_add_i32 s10, s27, s13
	global_load_lds_dwordx4 v[218:219], off
	v_lshl_add_u64 v[218:219], s[8:9], 0, v[146:147]
	s_mov_b32 m0, s10
	s_nop 0
	global_load_lds_dwordx4 v[218:219], off
	v_lshl_add_u64 v[218:219], s[8:9], 0, v[150:151]
	s_add_i32 m0, s10, 0x2000
	s_nop 0
	global_load_lds_dwordx4 v[218:219], off
	v_lshl_add_u64 v[218:219], v[222:223], 0, s[34:35]
	s_mov_b32 m0, s61
	s_nop 0
	global_load_lds_dwordx4 v[218:219], off
	v_lshl_add_u64 v[218:219], v[224:225], 0, s[34:35]
	s_mov_b32 m0, s62
	s_nop 0
	global_load_lds_dwordx4 v[218:219], off
	s_waitcnt vmcnt(8) lgkmcnt(0)
	s_barrier
	v_mfma_f32_16x16x32_bf16 v[60:63], v[128:131], v[186:189], v[60:63]
	v_mfma_f32_16x16x32_bf16 v[56:59], v[136:139], v[186:189], v[56:59]
	v_mfma_f32_16x16x32_bf16 v[44:47], v[128:131], v[194:197], v[44:47]
	v_mfma_f32_16x16x32_bf16 v[40:43], v[136:139], v[194:197], v[40:43]
	v_mfma_f32_16x16x32_bf16 v[28:31], v[128:131], v[202:205], v[28:31]
	v_mfma_f32_16x16x32_bf16 v[24:27], v[136:139], v[202:205], v[24:27]
	v_mfma_f32_16x16x32_bf16 v[12:15], v[128:131], v[210:213], v[12:15]
	v_mfma_f32_16x16x32_bf16 v[8:11], v[136:139], v[210:213], v[8:11]
	v_mfma_f32_16x16x32_bf16 v[60:63], v[132:135], v[190:193], v[60:63]
	v_mfma_f32_16x16x32_bf16 v[56:59], v[140:143], v[190:193], v[56:59]
	v_mfma_f32_16x16x32_bf16 v[44:47], v[132:135], v[198:201], v[44:47]
	v_mfma_f32_16x16x32_bf16 v[40:43], v[140:143], v[198:201], v[40:43]
	v_mfma_f32_16x16x32_bf16 v[28:31], v[132:135], v[206:209], v[28:31]
	v_mfma_f32_16x16x32_bf16 v[24:27], v[140:143], v[206:209], v[24:27]
	v_mfma_f32_16x16x32_bf16 v[12:15], v[132:135], v[214:217], v[12:15]
	v_mfma_f32_16x16x32_bf16 v[8:11], v[140:143], v[214:217], v[8:11]
	v_mfma_f32_16x16x32_bf16 v[52:55], v[158:161], v[186:189], v[52:55]
	v_mfma_f32_16x16x32_bf16 v[48:51], v[178:181], v[186:189], v[48:51]
	v_mfma_f32_16x16x32_bf16 v[36:39], v[158:161], v[194:197], v[36:39]
	v_mfma_f32_16x16x32_bf16 v[32:35], v[178:181], v[194:197], v[32:35]
	v_mfma_f32_16x16x32_bf16 v[20:23], v[158:161], v[202:205], v[20:23]
	v_mfma_f32_16x16x32_bf16 v[16:19], v[178:181], v[202:205], v[16:19]
	v_mfma_f32_16x16x32_bf16 v[4:7], v[158:161], v[210:213], v[4:7]
	v_mfma_f32_16x16x32_bf16 v[0:3], v[178:181], v[210:213], v[0:3]
	v_mfma_f32_16x16x32_bf16 v[52:55], v[162:165], v[190:193], v[52:55]
	v_mfma_f32_16x16x32_bf16 v[48:51], v[182:185], v[190:193], v[48:51]
	v_mfma_f32_16x16x32_bf16 v[36:39], v[162:165], v[198:201], v[36:39]
	v_mfma_f32_16x16x32_bf16 v[32:35], v[182:185], v[198:201], v[32:35]
	v_mfma_f32_16x16x32_bf16 v[20:23], v[162:165], v[206:209], v[20:23]
	v_mfma_f32_16x16x32_bf16 v[16:19], v[182:185], v[206:209], v[16:19]
	v_mfma_f32_16x16x32_bf16 v[4:7], v[162:165], v[214:217], v[4:7]
	v_mfma_f32_16x16x32_bf16 v[0:3], v[182:185], v[214:217], v[0:3]
	s_barrier
	s_add_i32 s79, s79, 2
	s_add_u32 s55, s55, 0x100
	s_addc_u32 s78, s78, 0
	s_add_u32 s4, s4, 0x100
	s_addc_u32 s5, s5, 0
	s_cmp_gt_u32 s79, 13
	s_cbranch_scc0 .LBB0_343
	s_and_b64 vcc, exec, s[18:19]
	s_cbranch_vccz .LBB0_346
	s_barrier

.LBB0_818:
	s_add_u32 s5, s70, 0x100
	s_addc_u32 s61, s71, 0
	s_add_u32 s68, s68, 0x40080
	v_mov_b32_e32 v0, 0
	s_addc_u32 s69, s69, 0
	s_mov_b32 s91, -2
	s_waitcnt lgkmcnt(0)
	ds_read_b128 v[104:107], v229
	ds_read_b128 v[108:111], v229 offset:1024
	ds_read_b128 v[128:131], v229 offset:2048
	ds_read_b128 v[132:135], v229 offset:3072
	ds_read_b128 v[144:147], v230
	ds_read_b128 v[148:151], v230 offset:1024
	ds_read_b128 v[152:155], v230 offset:2048
	ds_read_b128 v[156:159], v230 offset:3072
	s_add_u32 s26, s68, 0xfffc0080
	s_addc_u32 s27, s69, -1
	s_cmp_eq_u32 s91, 12
	s_cselect_b32 s73, s63, s27
	s_cselect_b32 s72, s62, s26
	s_cselect_b32 s71, s65, s61
	s_cselect_b32 s70, s64, s5
	v_lshl_add_u64 v[204:205], s[68:69], 0, v[202:203]
	s_add_i32 m0, s28, 0xc000
	ds_read_b128 v[160:163], v231
	ds_read_b128 v[164:167], v231 offset:1024
	ds_read_b128 v[168:171], v231 offset:2048
	ds_read_b128 v[172:175], v231 offset:3072
	ds_read_b128 v[176:179], v231 offset:4096
	ds_read_b128 v[180:183], v231 offset:5120
	ds_read_b128 v[184:187], v231 offset:6144
	ds_read_b128 v[188:191], v231 offset:7168
	global_load_lds_dwordx4 v[204:205], off
	v_lshl_add_u64 v[204:205], s[68:69], 0, v[200:201]
	s_add_i32 m0, s28, 0xe000
	s_nop 0
	global_load_lds_dwordx4 v[204:205], off
	s_waitcnt vmcnt(8) lgkmcnt(0)
	s_barrier
	v_mfma_f32_16x16x32_bf16 v[140:143], v[104:107], v[160:163], 0
	v_mfma_f32_16x16x32_bf16 v[136:139], v[128:131], v[160:163], 0
	v_mfma_f32_16x16x32_bf16 v[116:119], v[104:107], v[168:171], 0
	v_mfma_f32_16x16x32_bf16 v[112:115], v[128:131], v[168:171], 0
	v_mfma_f32_16x16x32_bf16 v[92:95], v[104:107], v[176:179], 0
	v_mfma_f32_16x16x32_bf16 v[88:91], v[128:131], v[176:179], 0
	v_mfma_f32_16x16x32_bf16 v[76:79], v[104:107], v[184:187], 0
	v_mfma_f32_16x16x32_bf16 v[72:75], v[128:131], v[184:187], 0
	v_mfma_f32_16x16x32_bf16 v[140:143], v[108:111], v[164:167], v[140:143]
	v_mfma_f32_16x16x32_bf16 v[136:139], v[132:135], v[164:167], v[136:139]
	v_mfma_f32_16x16x32_bf16 v[116:119], v[108:111], v[172:175], v[116:119]
	v_mfma_f32_16x16x32_bf16 v[112:115], v[132:135], v[172:175], v[112:115]
	v_mfma_f32_16x16x32_bf16 v[92:95], v[108:111], v[180:183], v[92:95]
	v_mfma_f32_16x16x32_bf16 v[88:91], v[132:135], v[180:183], v[88:91]
	v_mfma_f32_16x16x32_bf16 v[76:79], v[108:111], v[188:191], v[76:79]
	v_mfma_f32_16x16x32_bf16 v[72:75], v[132:135], v[188:191], v[72:75]
	v_mfma_f32_16x16x32_bf16 v[124:127], v[144:147], v[160:163], 0
	v_mfma_f32_16x16x32_bf16 v[120:123], v[152:155], v[160:163], 0
	v_mfma_f32_16x16x32_bf16 v[100:103], v[144:147], v[168:171], 0
	v_mfma_f32_16x16x32_bf16 v[96:99], v[152:155], v[168:171], 0
	v_mfma_f32_16x16x32_bf16 v[84:87], v[144:147], v[176:179], 0
	v_mfma_f32_16x16x32_bf16 v[80:83], v[152:155], v[176:179], 0
	v_mfma_f32_16x16x32_bf16 v[68:71], v[144:147], v[184:187], 0
	v_mfma_f32_16x16x32_bf16 v[64:67], v[152:155], v[184:187], 0
	v_mfma_f32_16x16x32_bf16 v[124:127], v[148:151], v[164:167], v[124:127]
	v_mfma_f32_16x16x32_bf16 v[120:123], v[156:159], v[164:167], v[120:123]
	v_mfma_f32_16x16x32_bf16 v[100:103], v[148:151], v[172:175], v[100:103]
	v_mfma_f32_16x16x32_bf16 v[96:99], v[156:159], v[172:175], v[96:99]
	v_mfma_f32_16x16x32_bf16 v[84:87], v[148:151], v[180:183], v[84:87]
	v_mfma_f32_16x16x32_bf16 v[80:83], v[156:159], v[180:183], v[80:83]
	v_mfma_f32_16x16x32_bf16 v[68:71], v[148:151], v[188:191], v[68:71]
	v_mfma_f32_16x16x32_bf16 v[64:67], v[156:159], v[188:191], v[64:67]
	s_barrier
	s_add_i32 s26, s83, s3
	v_lshl_add_u64 v[204:205], s[70:71], 0, v[194:195]
	s_mov_b32 m0, s26
	ds_read_b128 v[160:163], v231 offset:16384
	ds_read_b128 v[164:167], v231 offset:17408
	ds_read_b128 v[168:171], v231 offset:18432
	ds_read_b128 v[172:175], v231 offset:19456
	ds_read_b128 v[176:179], v231 offset:20480
	ds_read_b128 v[180:183], v231 offset:21504
	ds_read_b128 v[184:187], v231 offset:22528
	ds_read_b128 v[188:191], v231 offset:23552
	global_load_lds_dwordx4 v[204:205], off
	s_add_i32 m0, s26, 0x2000
	s_add_u32 s26, s70, 0x40000
	v_lshl_add_u64 v[206:207], s[70:71], 0, v[198:199]
	s_addc_u32 s27, s71, 0
	s_add_i32 s77, s84, s3
	global_load_lds_dwordx4 v[206:207], off
	v_lshl_add_u64 v[208:209], s[26:27], 0, v[194:195]
	s_mov_b32 m0, s77
	v_lshl_add_u64 v[210:211], s[72:73], 0, v[196:197]
	global_load_lds_dwordx4 v[208:209], off
	v_lshl_add_u64 v[208:209], s[26:27], 0, v[198:199]
	s_add_i32 m0, s77, 0x2000
	s_nop 0
	global_load_lds_dwordx4 v[208:209], off
	v_lshl_add_u64 v[208:209], s[72:73], 0, v[192:193]
	s_mov_b32 m0, s28
	s_nop 0
	global_load_lds_dwordx4 v[208:209], off
	s_mov_b32 m0, s29
	s_nop 0
	global_load_lds_dwordx4 v[210:211], off
	s_waitcnt vmcnt(8) lgkmcnt(0)
	s_barrier
	v_mfma_f32_16x16x32_bf16 v[60:63], v[104:107], v[160:163], 0
	v_mfma_f32_16x16x32_bf16 v[56:59], v[128:131], v[160:163], 0
	v_mfma_f32_16x16x32_bf16 v[44:47], v[104:107], v[168:171], 0
	v_mfma_f32_16x16x32_bf16 v[40:43], v[128:131], v[168:171], 0
	v_mfma_f32_16x16x32_bf16 v[28:31], v[104:107], v[176:179], 0
	v_mfma_f32_16x16x32_bf16 v[24:27], v[128:131], v[176:179], 0
	v_mfma_f32_16x16x32_bf16 v[12:15], v[104:107], v[184:187], 0
	v_mfma_f32_16x16x32_bf16 v[8:11], v[128:131], v[184:187], 0
	v_mfma_f32_16x16x32_bf16 v[60:63], v[108:111], v[164:167], v[60:63]
	v_mfma_f32_16x16x32_bf16 v[56:59], v[132:135], v[164:167], v[56:59]
	v_mfma_f32_16x16x32_bf16 v[44:47], v[108:111], v[172:175], v[44:47]
	v_mfma_f32_16x16x32_bf16 v[40:43], v[132:135], v[172:175], v[40:43]
	v_mfma_f32_16x16x32_bf16 v[28:31], v[108:111], v[180:183], v[28:31]
	v_mfma_f32_16x16x32_bf16 v[24:27], v[132:135], v[180:183], v[24:27]
	v_mfma_f32_16x16x32_bf16 v[12:15], v[108:111], v[188:191], v[12:15]
	v_mfma_f32_16x16x32_bf16 v[8:11], v[132:135], v[188:191], v[8:11]
	v_mfma_f32_16x16x32_bf16 v[52:55], v[144:147], v[160:163], 0
	v_mfma_f32_16x16x32_bf16 v[48:51], v[152:155], v[160:163], 0
	v_mfma_f32_16x16x32_bf16 v[36:39], v[144:147], v[168:171], 0
	v_mfma_f32_16x16x32_bf16 v[32:35], v[152:155], v[168:171], 0
	v_mfma_f32_16x16x32_bf16 v[20:23], v[144:147], v[176:179], 0
	v_mfma_f32_16x16x32_bf16 v[16:19], v[152:155], v[176:179], 0
	v_mfma_f32_16x16x32_bf16 v[4:7], v[144:147], v[184:187], 0
	v_mfma_f32_16x16x32_bf16 v[0:3], v[152:155], v[184:187], 0
	v_mfma_f32_16x16x32_bf16 v[52:55], v[148:151], v[164:167], v[52:55]
	v_mfma_f32_16x16x32_bf16 v[48:51], v[156:159], v[164:167], v[48:51]
	v_mfma_f32_16x16x32_bf16 v[36:39], v[148:151], v[172:175], v[36:39]
	v_mfma_f32_16x16x32_bf16 v[32:35], v[156:159], v[172:175], v[32:35]
	v_mfma_f32_16x16x32_bf16 v[20:23], v[148:151], v[180:183], v[20:23]
	v_mfma_f32_16x16x32_bf16 v[16:19], v[156:159], v[180:183], v[16:19]
	v_mfma_f32_16x16x32_bf16 v[4:7], v[148:151], v[188:191], v[4:7]
	v_mfma_f32_16x16x32_bf16 v[0:3], v[156:159], v[188:191], v[0:3]
	s_barrier
	s_add_i32 s77, 0, 0x18000
	s_add_i32 s92, 0, 0x1c000
	v_add_u32_e32 v132, s77, v228
	v_add_u32_e32 v156, s92, v228
	ds_read_b128 v[104:107], v132
	ds_read_b128 v[108:111], v132 offset:1024
	ds_read_b128 v[128:131], v132 offset:2048
	ds_read_b128 v[132:135], v132 offset:3072
	ds_read_b128 v[144:147], v156
	ds_read_b128 v[148:151], v156 offset:1024
	ds_read_b128 v[152:155], v156 offset:2048
	ds_read_b128 v[156:159], v156 offset:3072
	s_add_u32 s26, s72, 0x40000
	s_addc_u32 s27, s73, 0
	s_mov_b32 m0, s30
	v_lshl_add_u64 v[212:213], s[26:27], 0, v[192:193]
	ds_read_b128 v[160:163], v231 offset:32768
	ds_read_b128 v[164:167], v231 offset:33792
	ds_read_b128 v[168:171], v231 offset:34816
	ds_read_b128 v[172:175], v231 offset:35840
	ds_read_b128 v[176:179], v231 offset:36864
	ds_read_b128 v[180:183], v231 offset:37888
	ds_read_b128 v[184:187], v231 offset:38912
	ds_read_b128 v[188:191], v231 offset:39936
	global_load_lds_dwordx4 v[212:213], off
	v_lshl_add_u64 v[212:213], s[26:27], 0, v[196:197]
	s_mov_b32 m0, s31
	s_nop 0
	global_load_lds_dwordx4 v[212:213], off
	s_waitcnt vmcnt(8) lgkmcnt(0)
	s_barrier
	v_mfma_f32_16x16x32_bf16 v[140:143], v[104:107], v[160:163], v[140:143]
	v_mfma_f32_16x16x32_bf16 v[136:139], v[128:131], v[160:163], v[136:139]
	v_mfma_f32_16x16x32_bf16 v[116:119], v[104:107], v[168:171], v[116:119]
	v_mfma_f32_16x16x32_bf16 v[112:115], v[128:131], v[168:171], v[112:115]
	v_mfma_f32_16x16x32_bf16 v[92:95], v[104:107], v[176:179], v[92:95]
	v_mfma_f32_16x16x32_bf16 v[88:91], v[128:131], v[176:179], v[88:91]
	v_mfma_f32_16x16x32_bf16 v[76:79], v[104:107], v[184:187], v[76:79]
	v_mfma_f32_16x16x32_bf16 v[72:75], v[128:131], v[184:187], v[72:75]
	v_mfma_f32_16x16x32_bf16 v[140:143], v[108:111], v[164:167], v[140:143]
	v_mfma_f32_16x16x32_bf16 v[136:139], v[132:135], v[164:167], v[136:139]
	v_mfma_f32_16x16x32_bf16 v[116:119], v[108:111], v[172:175], v[116:119]
	v_mfma_f32_16x16x32_bf16 v[112:115], v[132:135], v[172:175], v[112:115]
	v_mfma_f32_16x16x32_bf16 v[92:95], v[108:111], v[180:183], v[92:95]
	v_mfma_f32_16x16x32_bf16 v[88:91], v[132:135], v[180:183], v[88:91]
	v_mfma_f32_16x16x32_bf16 v[76:79], v[108:111], v[188:191], v[76:79]
	v_mfma_f32_16x16x32_bf16 v[72:75], v[132:135], v[188:191], v[72:75]
	v_mfma_f32_16x16x32_bf16 v[124:127], v[144:147], v[160:163], v[124:127]
	v_mfma_f32_16x16x32_bf16 v[120:123], v[152:155], v[160:163], v[120:123]
	v_mfma_f32_16x16x32_bf16 v[100:103], v[144:147], v[168:171], v[100:103]
	v_mfma_f32_16x16x32_bf16 v[96:99], v[152:155], v[168:171], v[96:99]
	v_mfma_f32_16x16x32_bf16 v[84:87], v[144:147], v[176:179], v[84:87]
	v_mfma_f32_16x16x32_bf16 v[80:83], v[152:155], v[176:179], v[80:83]
	v_mfma_f32_16x16x32_bf16 v[68:71], v[144:147], v[184:187], v[68:71]
	v_mfma_f32_16x16x32_bf16 v[64:67], v[152:155], v[184:187], v[64:67]
	v_mfma_f32_16x16x32_bf16 v[124:127], v[148:151], v[164:167], v[124:127]
	v_mfma_f32_16x16x32_bf16 v[120:123], v[156:159], v[164:167], v[120:123]
	v_mfma_f32_16x16x32_bf16 v[100:103], v[148:151], v[172:175], v[100:103]
	v_mfma_f32_16x16x32_bf16 v[96:99], v[156:159], v[172:175], v[96:99]
	v_mfma_f32_16x16x32_bf16 v[84:87], v[148:151], v[180:183], v[84:87]
	v_mfma_f32_16x16x32_bf16 v[80:83], v[156:159], v[180:183], v[80:83]
	v_mfma_f32_16x16x32_bf16 v[68:71], v[148:151], v[188:191], v[68:71]
	v_mfma_f32_16x16x32_bf16 v[64:67], v[156:159], v[188:191], v[64:67]
	s_barrier
	s_add_i32 s26, s77, s3
	v_lshl_add_u64 v[204:205], v[204:205], 0, s[10:11]
	s_mov_b32 m0, s26
	ds_read_b128 v[160:163], v231 offset:49152
	ds_read_b128 v[164:167], v231 offset:50176
	ds_read_b128 v[168:171], v231 offset:51200
	ds_read_b128 v[172:175], v231 offset:52224
	ds_read_b128 v[176:179], v231 offset:53248
	ds_read_b128 v[180:183], v231 offset:54272
	ds_read_b128 v[184:187], v231 offset:55296
	ds_read_b128 v[188:191], v231 offset:56320
	global_load_lds_dwordx4 v[204:205], off
	s_add_i32 m0, s26, 0x2000
	s_add_u32 s26, s70, 0x40080
	v_lshl_add_u64 v[204:205], v[206:207], 0, s[10:11]
	s_addc_u32 s27, s71, 0
	s_add_i32 s70, s92, s3
	global_load_lds_dwordx4 v[204:205], off
	v_lshl_add_u64 v[204:205], s[26:27], 0, v[194:195]
	s_mov_b32 m0, s70
	s_nop 0
	global_load_lds_dwordx4 v[204:205], off
	v_lshl_add_u64 v[204:205], s[26:27], 0, v[198:199]
	s_add_i32 m0, s70, 0x2000
	s_nop 0
	global_load_lds_dwordx4 v[204:205], off
	v_lshl_add_u64 v[204:205], v[208:209], 0, s[10:11]
	s_mov_b32 m0, s81
	s_nop 0
	global_load_lds_dwordx4 v[204:205], off
	v_lshl_add_u64 v[204:205], v[210:211], 0, s[10:11]
	s_mov_b32 m0, s82
	s_nop 0
	global_load_lds_dwordx4 v[204:205], off
	s_waitcnt vmcnt(8) lgkmcnt(0)
	s_barrier
	v_mfma_f32_16x16x32_bf16 v[60:63], v[104:107], v[160:163], v[60:63]
	v_mfma_f32_16x16x32_bf16 v[56:59], v[128:131], v[160:163], v[56:59]
	v_mfma_f32_16x16x32_bf16 v[44:47], v[104:107], v[168:171], v[44:47]
	v_mfma_f32_16x16x32_bf16 v[40:43], v[128:131], v[168:171], v[40:43]
	v_mfma_f32_16x16x32_bf16 v[28:31], v[104:107], v[176:179], v[28:31]
	v_mfma_f32_16x16x32_bf16 v[24:27], v[128:131], v[176:179], v[24:27]
	v_mfma_f32_16x16x32_bf16 v[12:15], v[104:107], v[184:187], v[12:15]
	v_mfma_f32_16x16x32_bf16 v[8:11], v[128:131], v[184:187], v[8:11]
	v_mfma_f32_16x16x32_bf16 v[60:63], v[108:111], v[164:167], v[60:63]
	v_mfma_f32_16x16x32_bf16 v[56:59], v[132:135], v[164:167], v[56:59]
	v_mfma_f32_16x16x32_bf16 v[44:47], v[108:111], v[172:175], v[44:47]
	v_mfma_f32_16x16x32_bf16 v[40:43], v[132:135], v[172:175], v[40:43]
	v_mfma_f32_16x16x32_bf16 v[28:31], v[108:111], v[180:183], v[28:31]
	v_mfma_f32_16x16x32_bf16 v[24:27], v[132:135], v[180:183], v[24:27]
	v_mfma_f32_16x16x32_bf16 v[12:15], v[108:111], v[188:191], v[12:15]
	v_mfma_f32_16x16x32_bf16 v[8:11], v[132:135], v[188:191], v[8:11]
	v_mfma_f32_16x16x32_bf16 v[52:55], v[144:147], v[160:163], v[52:55]
	v_mfma_f32_16x16x32_bf16 v[48:51], v[152:155], v[160:163], v[48:51]
	v_mfma_f32_16x16x32_bf16 v[36:39], v[144:147], v[168:171], v[36:39]
	v_mfma_f32_16x16x32_bf16 v[32:35], v[152:155], v[168:171], v[32:35]
	v_mfma_f32_16x16x32_bf16 v[20:23], v[144:147], v[176:179], v[20:23]
	v_mfma_f32_16x16x32_bf16 v[16:19], v[152:155], v[176:179], v[16:19]
	v_mfma_f32_16x16x32_bf16 v[4:7], v[144:147], v[184:187], v[4:7]
	v_mfma_f32_16x16x32_bf16 v[0:3], v[152:155], v[184:187], v[0:3]
	v_mfma_f32_16x16x32_bf16 v[52:55], v[148:151], v[164:167], v[52:55]
	v_mfma_f32_16x16x32_bf16 v[48:51], v[156:159], v[164:167], v[48:51]
	v_mfma_f32_16x16x32_bf16 v[36:39], v[148:151], v[172:175], v[36:39]
	v_mfma_f32_16x16x32_bf16 v[32:35], v[156:159], v[172:175], v[32:35]
	v_mfma_f32_16x16x32_bf16 v[20:23], v[148:151], v[180:183], v[20:23]
	v_mfma_f32_16x16x32_bf16 v[16:19], v[156:159], v[180:183], v[16:19]
	v_mfma_f32_16x16x32_bf16 v[4:7], v[148:151], v[188:191], v[4:7]
	v_mfma_f32_16x16x32_bf16 v[0:3], v[156:159], v[188:191], v[0:3]
	s_barrier
	s_add_i32 s91, s91, 2
	s_add_u32 s5, s5, 0x100
	s_addc_u32 s61, s61, 0
	s_add_u32 s68, s68, 0x100
	s_addc_u32 s69, s69, 0
.LBB0_819:
	ds_read_b128 v[104:107], v229
	ds_read_b128 v[108:111], v229 offset:1024
	ds_read_b128 v[128:131], v229 offset:2048
	ds_read_b128 v[132:135], v229 offset:3072
	ds_read_b128 v[144:147], v230
	ds_read_b128 v[148:151], v230 offset:1024
	ds_read_b128 v[152:155], v230 offset:2048
	ds_read_b128 v[156:159], v230 offset:3072
	s_add_u32 s26, s68, 0xfffc0080
	s_addc_u32 s27, s69, -1
	s_cmp_eq_u32 s91, 12
	s_cselect_b32 s73, s63, s27
	s_cselect_b32 s72, s62, s26
	s_cselect_b32 s71, s65, s61
	s_cselect_b32 s70, s64, s5
	v_lshl_add_u64 v[204:205], s[68:69], 0, v[202:203]
	s_add_i32 m0, s28, 0xc000
	ds_read_b128 v[160:163], v231
	ds_read_b128 v[164:167], v231 offset:1024
	ds_read_b128 v[168:171], v231 offset:2048
	ds_read_b128 v[172:175], v231 offset:3072
	ds_read_b128 v[176:179], v231 offset:4096
	ds_read_b128 v[180:183], v231 offset:5120
	ds_read_b128 v[184:187], v231 offset:6144
	ds_read_b128 v[188:191], v231 offset:7168
	global_load_lds_dwordx4 v[204:205], off
	v_lshl_add_u64 v[204:205], s[68:69], 0, v[200:201]
	s_add_i32 m0, s28, 0xe000
	s_nop 0
	global_load_lds_dwordx4 v[204:205], off
	s_waitcnt vmcnt(8) lgkmcnt(0)
	s_barrier
	v_mfma_f32_16x16x32_bf16 v[140:143], v[104:107], v[160:163], v[140:143]
	v_mfma_f32_16x16x32_bf16 v[136:139], v[128:131], v[160:163], v[136:139]
	v_mfma_f32_16x16x32_bf16 v[116:119], v[104:107], v[168:171], v[116:119]
	v_mfma_f32_16x16x32_bf16 v[112:115], v[128:131], v[168:171], v[112:115]
	v_mfma_f32_16x16x32_bf16 v[92:95], v[104:107], v[176:179], v[92:95]
	v_mfma_f32_16x16x32_bf16 v[88:91], v[128:131], v[176:179], v[88:91]
	v_mfma_f32_16x16x32_bf16 v[76:79], v[104:107], v[184:187], v[76:79]
	v_mfma_f32_16x16x32_bf16 v[72:75], v[128:131], v[184:187], v[72:75]
	v_mfma_f32_16x16x32_bf16 v[140:143], v[108:111], v[164:167], v[140:143]
	v_mfma_f32_16x16x32_bf16 v[136:139], v[132:135], v[164:167], v[136:139]
	v_mfma_f32_16x16x32_bf16 v[116:119], v[108:111], v[172:175], v[116:119]
	v_mfma_f32_16x16x32_bf16 v[112:115], v[132:135], v[172:175], v[112:115]
	v_mfma_f32_16x16x32_bf16 v[92:95], v[108:111], v[180:183], v[92:95]
	v_mfma_f32_16x16x32_bf16 v[88:91], v[132:135], v[180:183], v[88:91]
	v_mfma_f32_16x16x32_bf16 v[76:79], v[108:111], v[188:191], v[76:79]
	v_mfma_f32_16x16x32_bf16 v[72:75], v[132:135], v[188:191], v[72:75]
	v_mfma_f32_16x16x32_bf16 v[124:127], v[144:147], v[160:163], v[124:127]
	v_mfma_f32_16x16x32_bf16 v[120:123], v[152:155], v[160:163], v[120:123]
	v_mfma_f32_16x16x32_bf16 v[100:103], v[144:147], v[168:171], v[100:103]
	v_mfma_f32_16x16x32_bf16 v[96:99], v[152:155], v[168:171], v[96:99]
	v_mfma_f32_16x16x32_bf16 v[84:87], v[144:147], v[176:179], v[84:87]
	v_mfma_f32_16x16x32_bf16 v[80:83], v[152:155], v[176:179], v[80:83]
	v_mfma_f32_16x16x32_bf16 v[68:71], v[144:147], v[184:187], v[68:71]
	v_mfma_f32_16x16x32_bf16 v[64:67], v[152:155], v[184:187], v[64:67]
	v_mfma_f32_16x16x32_bf16 v[124:127], v[148:151], v[164:167], v[124:127]
	v_mfma_f32_16x16x32_bf16 v[120:123], v[156:159], v[164:167], v[120:123]
	v_mfma_f32_16x16x32_bf16 v[100:103], v[148:151], v[172:175], v[100:103]
	v_mfma_f32_16x16x32_bf16 v[96:99], v[156:159], v[172:175], v[96:99]
	v_mfma_f32_16x16x32_bf16 v[84:87], v[148:151], v[180:183], v[84:87]
	v_mfma_f32_16x16x32_bf16 v[80:83], v[156:159], v[180:183], v[80:83]
	v_mfma_f32_16x16x32_bf16 v[68:71], v[148:151], v[188:191], v[68:71]
	v_mfma_f32_16x16x32_bf16 v[64:67], v[156:159], v[188:191], v[64:67]
	s_barrier
	s_add_i32 s26, s83, s3
	v_lshl_add_u64 v[204:205], s[70:71], 0, v[194:195]
	s_mov_b32 m0, s26
	ds_read_b128 v[160:163], v231 offset:16384
	ds_read_b128 v[164:167], v231 offset:17408
	ds_read_b128 v[168:171], v231 offset:18432
	ds_read_b128 v[172:175], v231 offset:19456
	ds_read_b128 v[176:179], v231 offset:20480
	ds_read_b128 v[180:183], v231 offset:21504
	ds_read_b128 v[184:187], v231 offset:22528
	ds_read_b128 v[188:191], v231 offset:23552
	global_load_lds_dwordx4 v[204:205], off
	s_add_i32 m0, s26, 0x2000
	s_add_u32 s26, s70, 0x40000
	v_lshl_add_u64 v[206:207], s[70:71], 0, v[198:199]
	s_addc_u32 s27, s71, 0
	s_add_i32 s77, s84, s3
	global_load_lds_dwordx4 v[206:207], off
	v_lshl_add_u64 v[208:209], s[26:27], 0, v[194:195]
	s_mov_b32 m0, s77
	v_lshl_add_u64 v[210:211], s[72:73], 0, v[196:197]
	global_load_lds_dwordx4 v[208:209], off
	v_lshl_add_u64 v[208:209], s[26:27], 0, v[198:199]
	s_add_i32 m0, s77, 0x2000
	s_nop 0
	global_load_lds_dwordx4 v[208:209], off
	v_lshl_add_u64 v[208:209], s[72:73], 0, v[192:193]
	s_mov_b32 m0, s28
	s_nop 0
	global_load_lds_dwordx4 v[208:209], off
	s_mov_b32 m0, s29
	s_nop 0
	global_load_lds_dwordx4 v[210:211], off
	s_waitcnt vmcnt(8) lgkmcnt(0)
	s_barrier
	v_mfma_f32_16x16x32_bf16 v[60:63], v[104:107], v[160:163], v[60:63]
	v_mfma_f32_16x16x32_bf16 v[56:59], v[128:131], v[160:163], v[56:59]
	v_mfma_f32_16x16x32_bf16 v[44:47], v[104:107], v[168:171], v[44:47]
	v_mfma_f32_16x16x32_bf16 v[40:43], v[128:131], v[168:171], v[40:43]
	v_mfma_f32_16x16x32_bf16 v[28:31], v[104:107], v[176:179], v[28:31]
	v_mfma_f32_16x16x32_bf16 v[24:27], v[128:131], v[176:179], v[24:27]
	v_mfma_f32_16x16x32_bf16 v[12:15], v[104:107], v[184:187], v[12:15]
	v_mfma_f32_16x16x32_bf16 v[8:11], v[128:131], v[184:187], v[8:11]
	v_mfma_f32_16x16x32_bf16 v[60:63], v[108:111], v[164:167], v[60:63]
	v_mfma_f32_16x16x32_bf16 v[56:59], v[132:135], v[164:167], v[56:59]
	v_mfma_f32_16x16x32_bf16 v[44:47], v[108:111], v[172:175], v[44:47]
	v_mfma_f32_16x16x32_bf16 v[40:43], v[132:135], v[172:175], v[40:43]
	v_mfma_f32_16x16x32_bf16 v[28:31], v[108:111], v[180:183], v[28:31]
	v_mfma_f32_16x16x32_bf16 v[24:27], v[132:135], v[180:183], v[24:27]
	v_mfma_f32_16x16x32_bf16 v[12:15], v[108:111], v[188:191], v[12:15]
	v_mfma_f32_16x16x32_bf16 v[8:11], v[132:135], v[188:191], v[8:11]
	v_mfma_f32_16x16x32_bf16 v[52:55], v[144:147], v[160:163], v[52:55]
	v_mfma_f32_16x16x32_bf16 v[48:51], v[152:155], v[160:163], v[48:51]
	v_mfma_f32_16x16x32_bf16 v[36:39], v[144:147], v[168:171], v[36:39]
	v_mfma_f32_16x16x32_bf16 v[32:35], v[152:155], v[168:171], v[32:35]
	v_mfma_f32_16x16x32_bf16 v[20:23], v[144:147], v[176:179], v[20:23]
	v_mfma_f32_16x16x32_bf16 v[16:19], v[152:155], v[176:179], v[16:19]
	v_mfma_f32_16x16x32_bf16 v[4:7], v[144:147], v[184:187], v[4:7]
	v_mfma_f32_16x16x32_bf16 v[0:3], v[152:155], v[184:187], v[0:3]
	v_mfma_f32_16x16x32_bf16 v[52:55], v[148:151], v[164:167], v[52:55]
	v_mfma_f32_16x16x32_bf16 v[48:51], v[156:159], v[164:167], v[48:51]
	v_mfma_f32_16x16x32_bf16 v[36:39], v[148:151], v[172:175], v[36:39]
	v_mfma_f32_16x16x32_bf16 v[32:35], v[156:159], v[172:175], v[32:35]
	v_mfma_f32_16x16x32_bf16 v[20:23], v[148:151], v[180:183], v[20:23]
	v_mfma_f32_16x16x32_bf16 v[16:19], v[156:159], v[180:183], v[16:19]
	v_mfma_f32_16x16x32_bf16 v[4:7], v[148:151], v[188:191], v[4:7]
	v_mfma_f32_16x16x32_bf16 v[0:3], v[156:159], v[188:191], v[0:3]
	s_barrier
	s_add_i32 s77, 0, 0x18000
	s_add_i32 s92, 0, 0x1c000
	v_add_u32_e32 v132, s77, v228
	v_add_u32_e32 v156, s92, v228
	ds_read_b128 v[104:107], v132
	ds_read_b128 v[108:111], v132 offset:1024
	ds_read_b128 v[128:131], v132 offset:2048
	ds_read_b128 v[132:135], v132 offset:3072
	ds_read_b128 v[144:147], v156
	ds_read_b128 v[148:151], v156 offset:1024
	ds_read_b128 v[152:155], v156 offset:2048
	ds_read_b128 v[156:159], v156 offset:3072
	s_add_u32 s26, s72, 0x40000
	s_addc_u32 s27, s73, 0
	s_mov_b32 m0, s30
	v_lshl_add_u64 v[212:213], s[26:27], 0, v[192:193]
	ds_read_b128 v[160:163], v231 offset:32768
	ds_read_b128 v[164:167], v231 offset:33792
	ds_read_b128 v[168:171], v231 offset:34816
	ds_read_b128 v[172:175], v231 offset:35840
	ds_read_b128 v[176:179], v231 offset:36864
	ds_read_b128 v[180:183], v231 offset:37888
	ds_read_b128 v[184:187], v231 offset:38912
	ds_read_b128 v[188:191], v231 offset:39936
	global_load_lds_dwordx4 v[212:213], off
	v_lshl_add_u64 v[212:213], s[26:27], 0, v[196:197]
	s_mov_b32 m0, s31
	s_nop 0
	global_load_lds_dwordx4 v[212:213], off
	s_waitcnt vmcnt(8) lgkmcnt(0)
	s_barrier
	v_mfma_f32_16x16x32_bf16 v[140:143], v[104:107], v[160:163], v[140:143]
	v_mfma_f32_16x16x32_bf16 v[136:139], v[128:131], v[160:163], v[136:139]
	v_mfma_f32_16x16x32_bf16 v[116:119], v[104:107], v[168:171], v[116:119]
	v_mfma_f32_16x16x32_bf16 v[112:115], v[128:131], v[168:171], v[112:115]
	v_mfma_f32_16x16x32_bf16 v[92:95], v[104:107], v[176:179], v[92:95]
	v_mfma_f32_16x16x32_bf16 v[88:91], v[128:131], v[176:179], v[88:91]
	v_mfma_f32_16x16x32_bf16 v[76:79], v[104:107], v[184:187], v[76:79]
	v_mfma_f32_16x16x32_bf16 v[72:75], v[128:131], v[184:187], v[72:75]
	v_mfma_f32_16x16x32_bf16 v[140:143], v[108:111], v[164:167], v[140:143]
	v_mfma_f32_16x16x32_bf16 v[136:139], v[132:135], v[164:167], v[136:139]
	v_mfma_f32_16x16x32_bf16 v[116:119], v[108:111], v[172:175], v[116:119]
	v_mfma_f32_16x16x32_bf16 v[112:115], v[132:135], v[172:175], v[112:115]
	v_mfma_f32_16x16x32_bf16 v[92:95], v[108:111], v[180:183], v[92:95]
	v_mfma_f32_16x16x32_bf16 v[88:91], v[132:135], v[180:183], v[88:91]
	v_mfma_f32_16x16x32_bf16 v[76:79], v[108:111], v[188:191], v[76:79]
	v_mfma_f32_16x16x32_bf16 v[72:75], v[132:135], v[188:191], v[72:75]
	v_mfma_f32_16x16x32_bf16 v[124:127], v[144:147], v[160:163], v[124:127]
	v_mfma_f32_16x16x32_bf16 v[120:123], v[152:155], v[160:163], v[120:123]
	v_mfma_f32_16x16x32_bf16 v[100:103], v[144:147], v[168:171], v[100:103]
	v_mfma_f32_16x16x32_bf16 v[96:99], v[152:155], v[168:171], v[96:99]
	v_mfma_f32_16x16x32_bf16 v[84:87], v[144:147], v[176:179], v[84:87]
	v_mfma_f32_16x16x32_bf16 v[80:83], v[152:155], v[176:179], v[80:83]
	v_mfma_f32_16x16x32_bf16 v[68:71], v[144:147], v[184:187], v[68:71]
	v_mfma_f32_16x16x32_bf16 v[64:67], v[152:155], v[184:187], v[64:67]
	v_mfma_f32_16x16x32_bf16 v[124:127], v[148:151], v[164:167], v[124:127]
	v_mfma_f32_16x16x32_bf16 v[120:123], v[156:159], v[164:167], v[120:123]
	v_mfma_f32_16x16x32_bf16 v[100:103], v[148:151], v[172:175], v[100:103]
	v_mfma_f32_16x16x32_bf16 v[96:99], v[156:159], v[172:175], v[96:99]
	v_mfma_f32_16x16x32_bf16 v[84:87], v[148:151], v[180:183], v[84:87]
	v_mfma_f32_16x16x32_bf16 v[80:83], v[156:159], v[180:183], v[80:83]
	v_mfma_f32_16x16x32_bf16 v[68:71], v[148:151], v[188:191], v[68:71]
	v_mfma_f32_16x16x32_bf16 v[64:67], v[156:159], v[188:191], v[64:67]
	s_barrier
	s_add_i32 s26, s77, s3
	v_lshl_add_u64 v[204:205], v[204:205], 0, s[10:11]
	s_mov_b32 m0, s26
	ds_read_b128 v[160:163], v231 offset:49152
	ds_read_b128 v[164:167], v231 offset:50176
	ds_read_b128 v[168:171], v231 offset:51200
	ds_read_b128 v[172:175], v231 offset:52224
	ds_read_b128 v[176:179], v231 offset:53248
	ds_read_b128 v[180:183], v231 offset:54272
	ds_read_b128 v[184:187], v231 offset:55296
	ds_read_b128 v[188:191], v231 offset:56320
	global_load_lds_dwordx4 v[204:205], off
	s_add_i32 m0, s26, 0x2000
	s_add_u32 s26, s70, 0x40080
	v_lshl_add_u64 v[204:205], v[206:207], 0, s[10:11]
	s_addc_u32 s27, s71, 0
	s_add_i32 s70, s92, s3
	global_load_lds_dwordx4 v[204:205], off
	v_lshl_add_u64 v[204:205], s[26:27], 0, v[194:195]
	s_mov_b32 m0, s70
	s_nop 0
	global_load_lds_dwordx4 v[204:205], off
	v_lshl_add_u64 v[204:205], s[26:27], 0, v[198:199]
	s_add_i32 m0, s70, 0x2000
	s_nop 0
	global_load_lds_dwordx4 v[204:205], off
	v_lshl_add_u64 v[204:205], v[208:209], 0, s[10:11]
	s_mov_b32 m0, s81
	s_nop 0
	global_load_lds_dwordx4 v[204:205], off
	v_lshl_add_u64 v[204:205], v[210:211], 0, s[10:11]
	s_mov_b32 m0, s82
	s_nop 0
	global_load_lds_dwordx4 v[204:205], off
	s_waitcnt vmcnt(8) lgkmcnt(0)
	s_barrier
	v_mfma_f32_16x16x32_bf16 v[60:63], v[104:107], v[160:163], v[60:63]
	v_mfma_f32_16x16x32_bf16 v[56:59], v[128:131], v[160:163], v[56:59]
	v_mfma_f32_16x16x32_bf16 v[44:47], v[104:107], v[168:171], v[44:47]
	v_mfma_f32_16x16x32_bf16 v[40:43], v[128:131], v[168:171], v[40:43]
	v_mfma_f32_16x16x32_bf16 v[28:31], v[104:107], v[176:179], v[28:31]
	v_mfma_f32_16x16x32_bf16 v[24:27], v[128:131], v[176:179], v[24:27]
	v_mfma_f32_16x16x32_bf16 v[12:15], v[104:107], v[184:187], v[12:15]
	v_mfma_f32_16x16x32_bf16 v[8:11], v[128:131], v[184:187], v[8:11]
	v_mfma_f32_16x16x32_bf16 v[60:63], v[108:111], v[164:167], v[60:63]
	v_mfma_f32_16x16x32_bf16 v[56:59], v[132:135], v[164:167], v[56:59]
	v_mfma_f32_16x16x32_bf16 v[44:47], v[108:111], v[172:175], v[44:47]
	v_mfma_f32_16x16x32_bf16 v[40:43], v[132:135], v[172:175], v[40:43]
	v_mfma_f32_16x16x32_bf16 v[28:31], v[108:111], v[180:183], v[28:31]
	v_mfma_f32_16x16x32_bf16 v[24:27], v[132:135], v[180:183], v[24:27]
	v_mfma_f32_16x16x32_bf16 v[12:15], v[108:111], v[188:191], v[12:15]
	v_mfma_f32_16x16x32_bf16 v[8:11], v[132:135], v[188:191], v[8:11]
	v_mfma_f32_16x16x32_bf16 v[52:55], v[144:147], v[160:163], v[52:55]
	v_mfma_f32_16x16x32_bf16 v[48:51], v[152:155], v[160:163], v[48:51]
	v_mfma_f32_16x16x32_bf16 v[36:39], v[144:147], v[168:171], v[36:39]
	v_mfma_f32_16x16x32_bf16 v[32:35], v[152:155], v[168:171], v[32:35]
	v_mfma_f32_16x16x32_bf16 v[20:23], v[144:147], v[176:179], v[20:23]
	v_mfma_f32_16x16x32_bf16 v[16:19], v[152:155], v[176:179], v[16:19]
	v_mfma_f32_16x16x32_bf16 v[4:7], v[144:147], v[184:187], v[4:7]
	v_mfma_f32_16x16x32_bf16 v[0:3], v[152:155], v[184:187], v[0:3]
	v_mfma_f32_16x16x32_bf16 v[52:55], v[148:151], v[164:167], v[52:55]
	v_mfma_f32_16x16x32_bf16 v[48:51], v[156:159], v[164:167], v[48:51]
	v_mfma_f32_16x16x32_bf16 v[36:39], v[148:151], v[172:175], v[36:39]
	v_mfma_f32_16x16x32_bf16 v[32:35], v[156:159], v[172:175], v[32:35]
	v_mfma_f32_16x16x32_bf16 v[20:23], v[148:151], v[180:183], v[20:23]
	v_mfma_f32_16x16x32_bf16 v[16:19], v[156:159], v[180:183], v[16:19]
	v_mfma_f32_16x16x32_bf16 v[4:7], v[148:151], v[188:191], v[4:7]
	v_mfma_f32_16x16x32_bf16 v[0:3], v[156:159], v[188:191], v[0:3]
	s_barrier
	s_add_i32 s91, s91, 2
	s_add_u32 s5, s5, 0x100
	s_addc_u32 s61, s61, 0
	s_add_u32 s68, s68, 0x100
	s_addc_u32 s69, s69, 0
	s_cmp_gt_u32 s91, 13
	s_cbranch_scc0 .LBB0_819
	s_and_b64 vcc, exec, s[8:9]
	s_cbranch_vccz .LBB0_822
	s_barrier

.LBB0_952:
	s_add_u32 s7, s10, 0x100
	s_addc_u32 s31, s11, 0
	s_add_u32 s8, s8, 0x40080
	v_mov_b32_e32 v2, 0
	s_addc_u32 s9, s9, 0
	s_mov_b32 s51, -2
	ds_read_b128 v[130:133], v167
	ds_read_b128 v[134:137], v167 offset:1024
	ds_read_b128 v[138:141], v167 offset:2048
	ds_read_b128 v[142:145], v167 offset:3072
	ds_read_b128 v[160:163], v168
	ds_read_b128 v[172:175], v168 offset:1024
	ds_read_b128 v[176:179], v168 offset:2048
	ds_read_b128 v[180:183], v168 offset:3072
	s_add_u32 s10, s8, 0xfffc0080
	s_addc_u32 s11, s9, -1
	s_cmp_eq_u32 s51, 12
	s_cselect_b32 s59, s53, s11
	s_cselect_b32 s58, s52, s10
	s_cselect_b32 s11, s57, s31
	s_cselect_b32 s10, s56, s7
	v_lshl_add_u64 v[164:165], s[8:9], 0, v[158:159]
	s_add_i32 m0, s84, 0xc000
	ds_read_b128 v[184:187], v169
	ds_read_b128 v[188:191], v169 offset:1024
	ds_read_b128 v[192:195], v169 offset:2048
	ds_read_b128 v[196:199], v169 offset:3072
	ds_read_b128 v[200:203], v169 offset:4096
	ds_read_b128 v[204:207], v169 offset:5120
	ds_read_b128 v[208:211], v169 offset:6144
	ds_read_b128 v[212:215], v169 offset:7168
	global_load_lds_dwordx4 v[164:165], off
	v_lshl_add_u64 v[164:165], s[8:9], 0, v[156:157]
	s_add_i32 m0, s84, 0xe000
	s_nop 0
	global_load_lds_dwordx4 v[164:165], off
	s_waitcnt vmcnt(8) lgkmcnt(0)
	s_barrier
	v_mfma_f32_16x16x32_bf16 v[126:129], v[130:133], v[184:187], 0
	v_mfma_f32_16x16x32_bf16 v[122:125], v[138:141], v[184:187], 0
	v_mfma_f32_16x16x32_bf16 v[110:113], v[130:133], v[192:195], 0
	v_mfma_f32_16x16x32_bf16 v[106:109], v[138:141], v[192:195], 0
	v_mfma_f32_16x16x32_bf16 v[94:97], v[130:133], v[200:203], 0
	v_mfma_f32_16x16x32_bf16 v[90:93], v[138:141], v[200:203], 0
	v_mfma_f32_16x16x32_bf16 v[78:81], v[130:133], v[208:211], 0
	v_mfma_f32_16x16x32_bf16 v[74:77], v[138:141], v[208:211], 0
	v_mfma_f32_16x16x32_bf16 v[126:129], v[134:137], v[188:191], v[126:129]
	v_mfma_f32_16x16x32_bf16 v[122:125], v[142:145], v[188:191], v[122:125]
	v_mfma_f32_16x16x32_bf16 v[110:113], v[134:137], v[196:199], v[110:113]
	v_mfma_f32_16x16x32_bf16 v[106:109], v[142:145], v[196:199], v[106:109]
	v_mfma_f32_16x16x32_bf16 v[94:97], v[134:137], v[204:207], v[94:97]
	v_mfma_f32_16x16x32_bf16 v[90:93], v[142:145], v[204:207], v[90:93]
	v_mfma_f32_16x16x32_bf16 v[78:81], v[134:137], v[212:215], v[78:81]
	v_mfma_f32_16x16x32_bf16 v[74:77], v[142:145], v[212:215], v[74:77]
	v_mfma_f32_16x16x32_bf16 v[118:121], v[160:163], v[184:187], 0
	v_mfma_f32_16x16x32_bf16 v[114:117], v[176:179], v[184:187], 0
	v_mfma_f32_16x16x32_bf16 v[102:105], v[160:163], v[192:195], 0
	v_mfma_f32_16x16x32_bf16 v[98:101], v[176:179], v[192:195], 0
	v_mfma_f32_16x16x32_bf16 v[86:89], v[160:163], v[200:203], 0
	v_mfma_f32_16x16x32_bf16 v[82:85], v[176:179], v[200:203], 0
	v_mfma_f32_16x16x32_bf16 v[70:73], v[160:163], v[208:211], 0
	v_mfma_f32_16x16x32_bf16 v[66:69], v[176:179], v[208:211], 0
	v_mfma_f32_16x16x32_bf16 v[118:121], v[172:175], v[188:191], v[118:121]
	v_mfma_f32_16x16x32_bf16 v[114:117], v[180:183], v[188:191], v[114:117]
	v_mfma_f32_16x16x32_bf16 v[102:105], v[172:175], v[196:199], v[102:105]
	v_mfma_f32_16x16x32_bf16 v[98:101], v[180:183], v[196:199], v[98:101]
	v_mfma_f32_16x16x32_bf16 v[86:89], v[172:175], v[204:207], v[86:89]
	v_mfma_f32_16x16x32_bf16 v[82:85], v[180:183], v[204:207], v[82:85]
	v_mfma_f32_16x16x32_bf16 v[70:73], v[172:175], v[212:215], v[70:73]
	v_mfma_f32_16x16x32_bf16 v[66:69], v[180:183], v[212:215], v[66:69]
	s_barrier
	s_add_i32 s26, s94, s39
	v_lshl_add_u64 v[164:165], s[10:11], 0, v[148:149]
	s_mov_b32 m0, s26
	ds_read_b128 v[184:187], v169 offset:16384
	ds_read_b128 v[188:191], v169 offset:17408
	ds_read_b128 v[192:195], v169 offset:18432
	ds_read_b128 v[196:199], v169 offset:19456
	ds_read_b128 v[200:203], v169 offset:20480
	ds_read_b128 v[204:207], v169 offset:21504
	ds_read_b128 v[208:211], v169 offset:22528
	ds_read_b128 v[212:215], v169 offset:23552
	global_load_lds_dwordx4 v[164:165], off
	s_add_i32 m0, s26, 0x2000
	s_add_u32 s26, s10, 0x40000
	v_lshl_add_u64 v[216:217], s[10:11], 0, v[152:153]
	s_addc_u32 s27, s11, 0
	s_add_i32 s60, s95, s39
	global_load_lds_dwordx4 v[216:217], off
	v_lshl_add_u64 v[218:219], s[26:27], 0, v[148:149]
	s_mov_b32 m0, s60
	v_lshl_add_u64 v[220:221], s[58:59], 0, v[150:151]
	global_load_lds_dwordx4 v[218:219], off
	v_lshl_add_u64 v[218:219], s[26:27], 0, v[152:153]
	s_add_i32 m0, s60, 0x2000
	s_nop 0
	global_load_lds_dwordx4 v[218:219], off
	v_lshl_add_u64 v[218:219], s[58:59], 0, v[146:147]
	s_mov_b32 m0, s84
	s_nop 0
	global_load_lds_dwordx4 v[218:219], off
	s_mov_b32 m0, s85
	s_nop 0
	global_load_lds_dwordx4 v[220:221], off
	s_waitcnt vmcnt(8) lgkmcnt(0)
	s_barrier
	v_mfma_f32_16x16x32_bf16 v[62:65], v[130:133], v[184:187], 0
	v_mfma_f32_16x16x32_bf16 v[58:61], v[138:141], v[184:187], 0
	v_mfma_f32_16x16x32_bf16 v[46:49], v[130:133], v[192:195], 0
	v_mfma_f32_16x16x32_bf16 v[42:45], v[138:141], v[192:195], 0
	v_mfma_f32_16x16x32_bf16 v[30:33], v[130:133], v[200:203], 0
	v_mfma_f32_16x16x32_bf16 v[26:29], v[138:141], v[200:203], 0
	v_mfma_f32_16x16x32_bf16 v[14:17], v[130:133], v[208:211], 0
	v_mfma_f32_16x16x32_bf16 v[10:13], v[138:141], v[208:211], 0
	v_mfma_f32_16x16x32_bf16 v[62:65], v[134:137], v[188:191], v[62:65]
	v_mfma_f32_16x16x32_bf16 v[58:61], v[142:145], v[188:191], v[58:61]
	v_mfma_f32_16x16x32_bf16 v[46:49], v[134:137], v[196:199], v[46:49]
	v_mfma_f32_16x16x32_bf16 v[42:45], v[142:145], v[196:199], v[42:45]
	v_mfma_f32_16x16x32_bf16 v[30:33], v[134:137], v[204:207], v[30:33]
	v_mfma_f32_16x16x32_bf16 v[26:29], v[142:145], v[204:207], v[26:29]
	v_mfma_f32_16x16x32_bf16 v[14:17], v[134:137], v[212:215], v[14:17]
	v_mfma_f32_16x16x32_bf16 v[10:13], v[142:145], v[212:215], v[10:13]
	v_mfma_f32_16x16x32_bf16 v[54:57], v[160:163], v[184:187], 0
	v_mfma_f32_16x16x32_bf16 v[50:53], v[176:179], v[184:187], 0
	v_mfma_f32_16x16x32_bf16 v[38:41], v[160:163], v[192:195], 0
	v_mfma_f32_16x16x32_bf16 v[34:37], v[176:179], v[192:195], 0
	v_mfma_f32_16x16x32_bf16 v[22:25], v[160:163], v[200:203], 0
	v_mfma_f32_16x16x32_bf16 v[18:21], v[176:179], v[200:203], 0
	v_mfma_f32_16x16x32_bf16 v[6:9], v[160:163], v[208:211], 0
	v_mfma_f32_16x16x32_bf16 v[2:5], v[176:179], v[208:211], 0
	v_mfma_f32_16x16x32_bf16 v[54:57], v[172:175], v[188:191], v[54:57]
	v_mfma_f32_16x16x32_bf16 v[50:53], v[180:183], v[188:191], v[50:53]
	v_mfma_f32_16x16x32_bf16 v[38:41], v[172:175], v[196:199], v[38:41]
	v_mfma_f32_16x16x32_bf16 v[34:37], v[180:183], v[196:199], v[34:37]
	v_mfma_f32_16x16x32_bf16 v[22:25], v[172:175], v[204:207], v[22:25]
	v_mfma_f32_16x16x32_bf16 v[18:21], v[180:183], v[204:207], v[18:21]
	v_mfma_f32_16x16x32_bf16 v[6:9], v[172:175], v[212:215], v[6:9]
	v_mfma_f32_16x16x32_bf16 v[2:5], v[180:183], v[212:215], v[2:5]
	s_barrier
	s_add_i32 s60, 0, 0x18000
	v_add_u32_e32 v1, s60, v166
	s_add_i32 s61, 0, 0x1c000
	ds_read_b128 v[130:133], v1
	ds_read_b128 v[134:137], v1 offset:1024
	ds_read_b128 v[138:141], v1 offset:2048
	ds_read_b128 v[142:145], v1 offset:3072
	v_add_u32_e32 v1, s61, v166
	ds_read_b128 v[160:163], v1
	ds_read_b128 v[172:175], v1 offset:1024
	ds_read_b128 v[176:179], v1 offset:2048
	ds_read_b128 v[180:183], v1 offset:3072
	s_add_u32 s26, s58, 0x40000
	s_addc_u32 s27, s59, 0
	s_mov_b32 m0, s86
	v_lshl_add_u64 v[222:223], s[26:27], 0, v[146:147]
	ds_read_b128 v[184:187], v169 offset:32768
	ds_read_b128 v[188:191], v169 offset:33792
	ds_read_b128 v[192:195], v169 offset:34816
	ds_read_b128 v[196:199], v169 offset:35840
	ds_read_b128 v[200:203], v169 offset:36864
	ds_read_b128 v[204:207], v169 offset:37888
	ds_read_b128 v[208:211], v169 offset:38912
	ds_read_b128 v[212:215], v169 offset:39936
	global_load_lds_dwordx4 v[222:223], off
	v_lshl_add_u64 v[222:223], s[26:27], 0, v[150:151]
	s_mov_b32 m0, s87
	s_nop 0
	global_load_lds_dwordx4 v[222:223], off
	s_waitcnt vmcnt(8) lgkmcnt(0)
	s_barrier
	v_mfma_f32_16x16x32_bf16 v[126:129], v[130:133], v[184:187], v[126:129]
	v_mfma_f32_16x16x32_bf16 v[122:125], v[138:141], v[184:187], v[122:125]
	v_mfma_f32_16x16x32_bf16 v[110:113], v[130:133], v[192:195], v[110:113]
	v_mfma_f32_16x16x32_bf16 v[106:109], v[138:141], v[192:195], v[106:109]
	v_mfma_f32_16x16x32_bf16 v[94:97], v[130:133], v[200:203], v[94:97]
	v_mfma_f32_16x16x32_bf16 v[90:93], v[138:141], v[200:203], v[90:93]
	v_mfma_f32_16x16x32_bf16 v[78:81], v[130:133], v[208:211], v[78:81]
	v_mfma_f32_16x16x32_bf16 v[74:77], v[138:141], v[208:211], v[74:77]
	v_mfma_f32_16x16x32_bf16 v[126:129], v[134:137], v[188:191], v[126:129]
	v_mfma_f32_16x16x32_bf16 v[122:125], v[142:145], v[188:191], v[122:125]
	v_mfma_f32_16x16x32_bf16 v[110:113], v[134:137], v[196:199], v[110:113]
	v_mfma_f32_16x16x32_bf16 v[106:109], v[142:145], v[196:199], v[106:109]
	v_mfma_f32_16x16x32_bf16 v[94:97], v[134:137], v[204:207], v[94:97]
	v_mfma_f32_16x16x32_bf16 v[90:93], v[142:145], v[204:207], v[90:93]
	v_mfma_f32_16x16x32_bf16 v[78:81], v[134:137], v[212:215], v[78:81]
	v_mfma_f32_16x16x32_bf16 v[74:77], v[142:145], v[212:215], v[74:77]
	v_mfma_f32_16x16x32_bf16 v[118:121], v[160:163], v[184:187], v[118:121]
	v_mfma_f32_16x16x32_bf16 v[114:117], v[176:179], v[184:187], v[114:117]
	v_mfma_f32_16x16x32_bf16 v[102:105], v[160:163], v[192:195], v[102:105]
	v_mfma_f32_16x16x32_bf16 v[98:101], v[176:179], v[192:195], v[98:101]
	v_mfma_f32_16x16x32_bf16 v[86:89], v[160:163], v[200:203], v[86:89]
	v_mfma_f32_16x16x32_bf16 v[82:85], v[176:179], v[200:203], v[82:85]
	v_mfma_f32_16x16x32_bf16 v[70:73], v[160:163], v[208:211], v[70:73]
	v_mfma_f32_16x16x32_bf16 v[66:69], v[176:179], v[208:211], v[66:69]
	v_mfma_f32_16x16x32_bf16 v[118:121], v[172:175], v[188:191], v[118:121]
	v_mfma_f32_16x16x32_bf16 v[114:117], v[180:183], v[188:191], v[114:117]
	v_mfma_f32_16x16x32_bf16 v[102:105], v[172:175], v[196:199], v[102:105]
	v_mfma_f32_16x16x32_bf16 v[98:101], v[180:183], v[196:199], v[98:101]
	v_mfma_f32_16x16x32_bf16 v[86:89], v[172:175], v[204:207], v[86:89]
	v_mfma_f32_16x16x32_bf16 v[82:85], v[180:183], v[204:207], v[82:85]
	v_mfma_f32_16x16x32_bf16 v[70:73], v[172:175], v[212:215], v[70:73]
	v_mfma_f32_16x16x32_bf16 v[66:69], v[180:183], v[212:215], v[66:69]
	s_barrier
	s_add_i32 s26, s60, s39
	v_lshl_add_u64 v[164:165], v[164:165], 0, s[18:19]
	s_mov_b32 m0, s26
	ds_read_b128 v[184:187], v169 offset:49152
	ds_read_b128 v[188:191], v169 offset:50176
	ds_read_b128 v[192:195], v169 offset:51200
	ds_read_b128 v[196:199], v169 offset:52224
	ds_read_b128 v[200:203], v169 offset:53248
	ds_read_b128 v[204:207], v169 offset:54272
	ds_read_b128 v[208:211], v169 offset:55296
	ds_read_b128 v[212:215], v169 offset:56320
	global_load_lds_dwordx4 v[164:165], off
	s_add_i32 m0, s26, 0x2000
	s_add_u32 s10, s10, 0x40080
	v_lshl_add_u64 v[164:165], v[216:217], 0, s[18:19]
	s_addc_u32 s11, s11, 0
	s_add_i32 s26, s61, s39
	global_load_lds_dwordx4 v[164:165], off
	v_lshl_add_u64 v[164:165], s[10:11], 0, v[148:149]
	s_mov_b32 m0, s26
	s_nop 0
	global_load_lds_dwordx4 v[164:165], off
	v_lshl_add_u64 v[164:165], s[10:11], 0, v[152:153]
	s_add_i32 m0, s26, 0x2000
	s_nop 0
	global_load_lds_dwordx4 v[164:165], off
	v_lshl_add_u64 v[164:165], v[218:219], 0, s[18:19]
	s_mov_b32 m0, s91
	s_nop 0
	global_load_lds_dwordx4 v[164:165], off
	v_lshl_add_u64 v[164:165], v[220:221], 0, s[18:19]
	s_mov_b32 m0, s92
	s_nop 0
	global_load_lds_dwordx4 v[164:165], off
	s_waitcnt vmcnt(8) lgkmcnt(0)
	s_barrier
	v_mfma_f32_16x16x32_bf16 v[62:65], v[130:133], v[184:187], v[62:65]
	v_mfma_f32_16x16x32_bf16 v[58:61], v[138:141], v[184:187], v[58:61]
	v_mfma_f32_16x16x32_bf16 v[46:49], v[130:133], v[192:195], v[46:49]
	v_mfma_f32_16x16x32_bf16 v[42:45], v[138:141], v[192:195], v[42:45]
	v_mfma_f32_16x16x32_bf16 v[30:33], v[130:133], v[200:203], v[30:33]
	v_mfma_f32_16x16x32_bf16 v[26:29], v[138:141], v[200:203], v[26:29]
	v_mfma_f32_16x16x32_bf16 v[14:17], v[130:133], v[208:211], v[14:17]
	v_mfma_f32_16x16x32_bf16 v[10:13], v[138:141], v[208:211], v[10:13]
	v_mfma_f32_16x16x32_bf16 v[62:65], v[134:137], v[188:191], v[62:65]
	v_mfma_f32_16x16x32_bf16 v[58:61], v[142:145], v[188:191], v[58:61]
	v_mfma_f32_16x16x32_bf16 v[46:49], v[134:137], v[196:199], v[46:49]
	v_mfma_f32_16x16x32_bf16 v[42:45], v[142:145], v[196:199], v[42:45]
	v_mfma_f32_16x16x32_bf16 v[30:33], v[134:137], v[204:207], v[30:33]
	v_mfma_f32_16x16x32_bf16 v[26:29], v[142:145], v[204:207], v[26:29]
	v_mfma_f32_16x16x32_bf16 v[14:17], v[134:137], v[212:215], v[14:17]
	v_mfma_f32_16x16x32_bf16 v[10:13], v[142:145], v[212:215], v[10:13]
	v_mfma_f32_16x16x32_bf16 v[54:57], v[160:163], v[184:187], v[54:57]
	v_mfma_f32_16x16x32_bf16 v[50:53], v[176:179], v[184:187], v[50:53]
	v_mfma_f32_16x16x32_bf16 v[38:41], v[160:163], v[192:195], v[38:41]
	v_mfma_f32_16x16x32_bf16 v[34:37], v[176:179], v[192:195], v[34:37]
	v_mfma_f32_16x16x32_bf16 v[22:25], v[160:163], v[200:203], v[22:25]
	v_mfma_f32_16x16x32_bf16 v[18:21], v[176:179], v[200:203], v[18:21]
	v_mfma_f32_16x16x32_bf16 v[6:9], v[160:163], v[208:211], v[6:9]
	v_mfma_f32_16x16x32_bf16 v[2:5], v[176:179], v[208:211], v[2:5]
	v_mfma_f32_16x16x32_bf16 v[54:57], v[172:175], v[188:191], v[54:57]
	v_mfma_f32_16x16x32_bf16 v[50:53], v[180:183], v[188:191], v[50:53]
	v_mfma_f32_16x16x32_bf16 v[38:41], v[172:175], v[196:199], v[38:41]
	v_mfma_f32_16x16x32_bf16 v[34:37], v[180:183], v[196:199], v[34:37]
	v_mfma_f32_16x16x32_bf16 v[22:25], v[172:175], v[204:207], v[22:25]
	v_mfma_f32_16x16x32_bf16 v[18:21], v[180:183], v[204:207], v[18:21]
	v_mfma_f32_16x16x32_bf16 v[6:9], v[172:175], v[212:215], v[6:9]
	v_mfma_f32_16x16x32_bf16 v[2:5], v[180:183], v[212:215], v[2:5]
	s_barrier
	s_add_i32 s51, s51, 2
	s_add_u32 s7, s7, 0x100
	s_addc_u32 s31, s31, 0
	s_add_u32 s8, s8, 0x100
	s_addc_u32 s9, s9, 0
.LBB0_953:
	ds_read_b128 v[130:133], v167
	ds_read_b128 v[134:137], v167 offset:1024
	ds_read_b128 v[138:141], v167 offset:2048
	ds_read_b128 v[142:145], v167 offset:3072
	ds_read_b128 v[160:163], v168
	ds_read_b128 v[172:175], v168 offset:1024
	ds_read_b128 v[176:179], v168 offset:2048
	ds_read_b128 v[180:183], v168 offset:3072
	s_add_u32 s10, s8, 0xfffc0080
	s_addc_u32 s11, s9, -1
	s_cmp_eq_u32 s51, 12
	s_cselect_b32 s59, s53, s11
	s_cselect_b32 s58, s52, s10
	s_cselect_b32 s11, s57, s31
	s_cselect_b32 s10, s56, s7
	v_lshl_add_u64 v[164:165], s[8:9], 0, v[158:159]
	s_add_i32 m0, s84, 0xc000
	ds_read_b128 v[184:187], v169
	ds_read_b128 v[188:191], v169 offset:1024
	ds_read_b128 v[192:195], v169 offset:2048
	ds_read_b128 v[196:199], v169 offset:3072
	ds_read_b128 v[200:203], v169 offset:4096
	ds_read_b128 v[204:207], v169 offset:5120
	ds_read_b128 v[208:211], v169 offset:6144
	ds_read_b128 v[212:215], v169 offset:7168
	global_load_lds_dwordx4 v[164:165], off
	v_lshl_add_u64 v[164:165], s[8:9], 0, v[156:157]
	s_add_i32 m0, s84, 0xe000
	s_nop 0
	global_load_lds_dwordx4 v[164:165], off
	s_waitcnt vmcnt(8) lgkmcnt(0)
	s_barrier
	v_mfma_f32_16x16x32_bf16 v[126:129], v[130:133], v[184:187], v[126:129]
	v_mfma_f32_16x16x32_bf16 v[122:125], v[138:141], v[184:187], v[122:125]
	v_mfma_f32_16x16x32_bf16 v[110:113], v[130:133], v[192:195], v[110:113]
	v_mfma_f32_16x16x32_bf16 v[106:109], v[138:141], v[192:195], v[106:109]
	v_mfma_f32_16x16x32_bf16 v[94:97], v[130:133], v[200:203], v[94:97]
	v_mfma_f32_16x16x32_bf16 v[90:93], v[138:141], v[200:203], v[90:93]
	v_mfma_f32_16x16x32_bf16 v[78:81], v[130:133], v[208:211], v[78:81]
	v_mfma_f32_16x16x32_bf16 v[74:77], v[138:141], v[208:211], v[74:77]
	v_mfma_f32_16x16x32_bf16 v[126:129], v[134:137], v[188:191], v[126:129]
	v_mfma_f32_16x16x32_bf16 v[122:125], v[142:145], v[188:191], v[122:125]
	v_mfma_f32_16x16x32_bf16 v[110:113], v[134:137], v[196:199], v[110:113]
	v_mfma_f32_16x16x32_bf16 v[106:109], v[142:145], v[196:199], v[106:109]
	v_mfma_f32_16x16x32_bf16 v[94:97], v[134:137], v[204:207], v[94:97]
	v_mfma_f32_16x16x32_bf16 v[90:93], v[142:145], v[204:207], v[90:93]
	v_mfma_f32_16x16x32_bf16 v[78:81], v[134:137], v[212:215], v[78:81]
	v_mfma_f32_16x16x32_bf16 v[74:77], v[142:145], v[212:215], v[74:77]
	v_mfma_f32_16x16x32_bf16 v[118:121], v[160:163], v[184:187], v[118:121]
	v_mfma_f32_16x16x32_bf16 v[114:117], v[176:179], v[184:187], v[114:117]
	v_mfma_f32_16x16x32_bf16 v[102:105], v[160:163], v[192:195], v[102:105]
	v_mfma_f32_16x16x32_bf16 v[98:101], v[176:179], v[192:195], v[98:101]
	v_mfma_f32_16x16x32_bf16 v[86:89], v[160:163], v[200:203], v[86:89]
	v_mfma_f32_16x16x32_bf16 v[82:85], v[176:179], v[200:203], v[82:85]
	v_mfma_f32_16x16x32_bf16 v[70:73], v[160:163], v[208:211], v[70:73]
	v_mfma_f32_16x16x32_bf16 v[66:69], v[176:179], v[208:211], v[66:69]
	v_mfma_f32_16x16x32_bf16 v[118:121], v[172:175], v[188:191], v[118:121]
	v_mfma_f32_16x16x32_bf16 v[114:117], v[180:183], v[188:191], v[114:117]
	v_mfma_f32_16x16x32_bf16 v[102:105], v[172:175], v[196:199], v[102:105]
	v_mfma_f32_16x16x32_bf16 v[98:101], v[180:183], v[196:199], v[98:101]
	v_mfma_f32_16x16x32_bf16 v[86:89], v[172:175], v[204:207], v[86:89]
	v_mfma_f32_16x16x32_bf16 v[82:85], v[180:183], v[204:207], v[82:85]
	v_mfma_f32_16x16x32_bf16 v[70:73], v[172:175], v[212:215], v[70:73]
	v_mfma_f32_16x16x32_bf16 v[66:69], v[180:183], v[212:215], v[66:69]
	s_barrier
	s_add_i32 s26, s94, s39
	v_lshl_add_u64 v[164:165], s[10:11], 0, v[148:149]
	s_mov_b32 m0, s26
	ds_read_b128 v[184:187], v169 offset:16384
	ds_read_b128 v[188:191], v169 offset:17408
	ds_read_b128 v[192:195], v169 offset:18432
	ds_read_b128 v[196:199], v169 offset:19456
	ds_read_b128 v[200:203], v169 offset:20480
	ds_read_b128 v[204:207], v169 offset:21504
	ds_read_b128 v[208:211], v169 offset:22528
	ds_read_b128 v[212:215], v169 offset:23552
	global_load_lds_dwordx4 v[164:165], off
	s_add_i32 m0, s26, 0x2000
	s_add_u32 s26, s10, 0x40000
	v_lshl_add_u64 v[216:217], s[10:11], 0, v[152:153]
	s_addc_u32 s27, s11, 0
	s_add_i32 s60, s95, s39
	global_load_lds_dwordx4 v[216:217], off
	v_lshl_add_u64 v[218:219], s[26:27], 0, v[148:149]
	s_mov_b32 m0, s60
	v_lshl_add_u64 v[220:221], s[58:59], 0, v[150:151]
	global_load_lds_dwordx4 v[218:219], off
	v_lshl_add_u64 v[218:219], s[26:27], 0, v[152:153]
	s_add_i32 m0, s60, 0x2000
	s_nop 0
	global_load_lds_dwordx4 v[218:219], off
	v_lshl_add_u64 v[218:219], s[58:59], 0, v[146:147]
	s_mov_b32 m0, s84
	s_nop 0
	global_load_lds_dwordx4 v[218:219], off
	s_mov_b32 m0, s85
	s_nop 0
	global_load_lds_dwordx4 v[220:221], off
	s_waitcnt vmcnt(8) lgkmcnt(0)
	s_barrier
	v_mfma_f32_16x16x32_bf16 v[62:65], v[130:133], v[184:187], v[62:65]
	v_mfma_f32_16x16x32_bf16 v[58:61], v[138:141], v[184:187], v[58:61]
	v_mfma_f32_16x16x32_bf16 v[46:49], v[130:133], v[192:195], v[46:49]
	v_mfma_f32_16x16x32_bf16 v[42:45], v[138:141], v[192:195], v[42:45]
	v_mfma_f32_16x16x32_bf16 v[30:33], v[130:133], v[200:203], v[30:33]
	v_mfma_f32_16x16x32_bf16 v[26:29], v[138:141], v[200:203], v[26:29]
	v_mfma_f32_16x16x32_bf16 v[14:17], v[130:133], v[208:211], v[14:17]
	v_mfma_f32_16x16x32_bf16 v[10:13], v[138:141], v[208:211], v[10:13]
	v_mfma_f32_16x16x32_bf16 v[62:65], v[134:137], v[188:191], v[62:65]
	v_mfma_f32_16x16x32_bf16 v[58:61], v[142:145], v[188:191], v[58:61]
	v_mfma_f32_16x16x32_bf16 v[46:49], v[134:137], v[196:199], v[46:49]
	v_mfma_f32_16x16x32_bf16 v[42:45], v[142:145], v[196:199], v[42:45]
	v_mfma_f32_16x16x32_bf16 v[30:33], v[134:137], v[204:207], v[30:33]
	v_mfma_f32_16x16x32_bf16 v[26:29], v[142:145], v[204:207], v[26:29]
	v_mfma_f32_16x16x32_bf16 v[14:17], v[134:137], v[212:215], v[14:17]
	v_mfma_f32_16x16x32_bf16 v[10:13], v[142:145], v[212:215], v[10:13]
	v_mfma_f32_16x16x32_bf16 v[54:57], v[160:163], v[184:187], v[54:57]
	v_mfma_f32_16x16x32_bf16 v[50:53], v[176:179], v[184:187], v[50:53]
	v_mfma_f32_16x16x32_bf16 v[38:41], v[160:163], v[192:195], v[38:41]
	v_mfma_f32_16x16x32_bf16 v[34:37], v[176:179], v[192:195], v[34:37]
	v_mfma_f32_16x16x32_bf16 v[22:25], v[160:163], v[200:203], v[22:25]
	v_mfma_f32_16x16x32_bf16 v[18:21], v[176:179], v[200:203], v[18:21]
	v_mfma_f32_16x16x32_bf16 v[6:9], v[160:163], v[208:211], v[6:9]
	v_mfma_f32_16x16x32_bf16 v[2:5], v[176:179], v[208:211], v[2:5]
	v_mfma_f32_16x16x32_bf16 v[54:57], v[172:175], v[188:191], v[54:57]
	v_mfma_f32_16x16x32_bf16 v[50:53], v[180:183], v[188:191], v[50:53]
	v_mfma_f32_16x16x32_bf16 v[38:41], v[172:175], v[196:199], v[38:41]
	v_mfma_f32_16x16x32_bf16 v[34:37], v[180:183], v[196:199], v[34:37]
	v_mfma_f32_16x16x32_bf16 v[22:25], v[172:175], v[204:207], v[22:25]
	v_mfma_f32_16x16x32_bf16 v[18:21], v[180:183], v[204:207], v[18:21]
	v_mfma_f32_16x16x32_bf16 v[6:9], v[172:175], v[212:215], v[6:9]
	v_mfma_f32_16x16x32_bf16 v[2:5], v[180:183], v[212:215], v[2:5]
	s_barrier
	s_add_i32 s60, 0, 0x18000
	v_add_u32_e32 v1, s60, v166
	s_add_i32 s61, 0, 0x1c000
	ds_read_b128 v[130:133], v1
	ds_read_b128 v[134:137], v1 offset:1024
	ds_read_b128 v[138:141], v1 offset:2048
	ds_read_b128 v[142:145], v1 offset:3072
	v_add_u32_e32 v1, s61, v166
	ds_read_b128 v[160:163], v1
	ds_read_b128 v[172:175], v1 offset:1024
	ds_read_b128 v[176:179], v1 offset:2048
	ds_read_b128 v[180:183], v1 offset:3072
	s_add_u32 s26, s58, 0x40000
	s_addc_u32 s27, s59, 0
	s_mov_b32 m0, s86
	v_lshl_add_u64 v[222:223], s[26:27], 0, v[146:147]
	ds_read_b128 v[184:187], v169 offset:32768
	ds_read_b128 v[188:191], v169 offset:33792
	ds_read_b128 v[192:195], v169 offset:34816
	ds_read_b128 v[196:199], v169 offset:35840
	ds_read_b128 v[200:203], v169 offset:36864
	ds_read_b128 v[204:207], v169 offset:37888
	ds_read_b128 v[208:211], v169 offset:38912
	ds_read_b128 v[212:215], v169 offset:39936
	global_load_lds_dwordx4 v[222:223], off
	v_lshl_add_u64 v[222:223], s[26:27], 0, v[150:151]
	s_mov_b32 m0, s87
	s_nop 0
	global_load_lds_dwordx4 v[222:223], off
	s_waitcnt vmcnt(8) lgkmcnt(0)
	s_barrier
	v_mfma_f32_16x16x32_bf16 v[126:129], v[130:133], v[184:187], v[126:129]
	v_mfma_f32_16x16x32_bf16 v[122:125], v[138:141], v[184:187], v[122:125]
	v_mfma_f32_16x16x32_bf16 v[110:113], v[130:133], v[192:195], v[110:113]
	v_mfma_f32_16x16x32_bf16 v[106:109], v[138:141], v[192:195], v[106:109]
	v_mfma_f32_16x16x32_bf16 v[94:97], v[130:133], v[200:203], v[94:97]
	v_mfma_f32_16x16x32_bf16 v[90:93], v[138:141], v[200:203], v[90:93]
	v_mfma_f32_16x16x32_bf16 v[78:81], v[130:133], v[208:211], v[78:81]
	v_mfma_f32_16x16x32_bf16 v[74:77], v[138:141], v[208:211], v[74:77]
	v_mfma_f32_16x16x32_bf16 v[126:129], v[134:137], v[188:191], v[126:129]
	v_mfma_f32_16x16x32_bf16 v[122:125], v[142:145], v[188:191], v[122:125]
	v_mfma_f32_16x16x32_bf16 v[110:113], v[134:137], v[196:199], v[110:113]
	v_mfma_f32_16x16x32_bf16 v[106:109], v[142:145], v[196:199], v[106:109]
	v_mfma_f32_16x16x32_bf16 v[94:97], v[134:137], v[204:207], v[94:97]
	v_mfma_f32_16x16x32_bf16 v[90:93], v[142:145], v[204:207], v[90:93]
	v_mfma_f32_16x16x32_bf16 v[78:81], v[134:137], v[212:215], v[78:81]
	v_mfma_f32_16x16x32_bf16 v[74:77], v[142:145], v[212:215], v[74:77]
	v_mfma_f32_16x16x32_bf16 v[118:121], v[160:163], v[184:187], v[118:121]
	v_mfma_f32_16x16x32_bf16 v[114:117], v[176:179], v[184:187], v[114:117]
	v_mfma_f32_16x16x32_bf16 v[102:105], v[160:163], v[192:195], v[102:105]
	v_mfma_f32_16x16x32_bf16 v[98:101], v[176:179], v[192:195], v[98:101]
	v_mfma_f32_16x16x32_bf16 v[86:89], v[160:163], v[200:203], v[86:89]
	v_mfma_f32_16x16x32_bf16 v[82:85], v[176:179], v[200:203], v[82:85]
	v_mfma_f32_16x16x32_bf16 v[70:73], v[160:163], v[208:211], v[70:73]
	v_mfma_f32_16x16x32_bf16 v[66:69], v[176:179], v[208:211], v[66:69]
	v_mfma_f32_16x16x32_bf16 v[118:121], v[172:175], v[188:191], v[118:121]
	v_mfma_f32_16x16x32_bf16 v[114:117], v[180:183], v[188:191], v[114:117]
	v_mfma_f32_16x16x32_bf16 v[102:105], v[172:175], v[196:199], v[102:105]
	v_mfma_f32_16x16x32_bf16 v[98:101], v[180:183], v[196:199], v[98:101]
	v_mfma_f32_16x16x32_bf16 v[86:89], v[172:175], v[204:207], v[86:89]
	v_mfma_f32_16x16x32_bf16 v[82:85], v[180:183], v[204:207], v[82:85]
	v_mfma_f32_16x16x32_bf16 v[70:73], v[172:175], v[212:215], v[70:73]
	v_mfma_f32_16x16x32_bf16 v[66:69], v[180:183], v[212:215], v[66:69]
	s_barrier
	s_add_i32 s26, s60, s39
	v_lshl_add_u64 v[164:165], v[164:165], 0, s[18:19]
	s_mov_b32 m0, s26
	ds_read_b128 v[184:187], v169 offset:49152
	ds_read_b128 v[188:191], v169 offset:50176
	ds_read_b128 v[192:195], v169 offset:51200
	ds_read_b128 v[196:199], v169 offset:52224
	ds_read_b128 v[200:203], v169 offset:53248
	ds_read_b128 v[204:207], v169 offset:54272
	ds_read_b128 v[208:211], v169 offset:55296
	ds_read_b128 v[212:215], v169 offset:56320
	global_load_lds_dwordx4 v[164:165], off
	s_add_i32 m0, s26, 0x2000
	s_add_u32 s10, s10, 0x40080
	v_lshl_add_u64 v[164:165], v[216:217], 0, s[18:19]
	s_addc_u32 s11, s11, 0
	s_add_i32 s26, s61, s39
	global_load_lds_dwordx4 v[164:165], off
	v_lshl_add_u64 v[164:165], s[10:11], 0, v[148:149]
	s_mov_b32 m0, s26
	s_nop 0
	global_load_lds_dwordx4 v[164:165], off
	v_lshl_add_u64 v[164:165], s[10:11], 0, v[152:153]
	s_add_i32 m0, s26, 0x2000
	s_nop 0
	global_load_lds_dwordx4 v[164:165], off
	v_lshl_add_u64 v[164:165], v[218:219], 0, s[18:19]
	s_mov_b32 m0, s91
	s_nop 0
	global_load_lds_dwordx4 v[164:165], off
	v_lshl_add_u64 v[164:165], v[220:221], 0, s[18:19]
	s_mov_b32 m0, s92
	s_nop 0
	global_load_lds_dwordx4 v[164:165], off
	s_waitcnt vmcnt(8) lgkmcnt(0)
	s_barrier
	v_mfma_f32_16x16x32_bf16 v[62:65], v[130:133], v[184:187], v[62:65]
	v_mfma_f32_16x16x32_bf16 v[58:61], v[138:141], v[184:187], v[58:61]
	v_mfma_f32_16x16x32_bf16 v[46:49], v[130:133], v[192:195], v[46:49]
	v_mfma_f32_16x16x32_bf16 v[42:45], v[138:141], v[192:195], v[42:45]
	v_mfma_f32_16x16x32_bf16 v[30:33], v[130:133], v[200:203], v[30:33]
	v_mfma_f32_16x16x32_bf16 v[26:29], v[138:141], v[200:203], v[26:29]
	v_mfma_f32_16x16x32_bf16 v[14:17], v[130:133], v[208:211], v[14:17]
	v_mfma_f32_16x16x32_bf16 v[10:13], v[138:141], v[208:211], v[10:13]
	v_mfma_f32_16x16x32_bf16 v[62:65], v[134:137], v[188:191], v[62:65]
	v_mfma_f32_16x16x32_bf16 v[58:61], v[142:145], v[188:191], v[58:61]
	v_mfma_f32_16x16x32_bf16 v[46:49], v[134:137], v[196:199], v[46:49]
	v_mfma_f32_16x16x32_bf16 v[42:45], v[142:145], v[196:199], v[42:45]
	v_mfma_f32_16x16x32_bf16 v[30:33], v[134:137], v[204:207], v[30:33]
	v_mfma_f32_16x16x32_bf16 v[26:29], v[142:145], v[204:207], v[26:29]
	v_mfma_f32_16x16x32_bf16 v[14:17], v[134:137], v[212:215], v[14:17]
	v_mfma_f32_16x16x32_bf16 v[10:13], v[142:145], v[212:215], v[10:13]
	v_mfma_f32_16x16x32_bf16 v[54:57], v[160:163], v[184:187], v[54:57]
	v_mfma_f32_16x16x32_bf16 v[50:53], v[176:179], v[184:187], v[50:53]
	v_mfma_f32_16x16x32_bf16 v[38:41], v[160:163], v[192:195], v[38:41]
	v_mfma_f32_16x16x32_bf16 v[34:37], v[176:179], v[192:195], v[34:37]
	v_mfma_f32_16x16x32_bf16 v[22:25], v[160:163], v[200:203], v[22:25]
	v_mfma_f32_16x16x32_bf16 v[18:21], v[176:179], v[200:203], v[18:21]
	v_mfma_f32_16x16x32_bf16 v[6:9], v[160:163], v[208:211], v[6:9]
	v_mfma_f32_16x16x32_bf16 v[2:5], v[176:179], v[208:211], v[2:5]
	v_mfma_f32_16x16x32_bf16 v[54:57], v[172:175], v[188:191], v[54:57]
	v_mfma_f32_16x16x32_bf16 v[50:53], v[180:183], v[188:191], v[50:53]
	v_mfma_f32_16x16x32_bf16 v[38:41], v[172:175], v[196:199], v[38:41]
	v_mfma_f32_16x16x32_bf16 v[34:37], v[180:183], v[196:199], v[34:37]
	v_mfma_f32_16x16x32_bf16 v[22:25], v[172:175], v[204:207], v[22:25]
	v_mfma_f32_16x16x32_bf16 v[18:21], v[180:183], v[204:207], v[18:21]
	v_mfma_f32_16x16x32_bf16 v[6:9], v[172:175], v[212:215], v[6:9]
	v_mfma_f32_16x16x32_bf16 v[2:5], v[180:183], v[212:215], v[2:5]
	s_barrier
	s_add_i32 s51, s51, 2
	s_add_u32 s7, s7, 0x100
	s_addc_u32 s31, s31, 0
	s_add_u32 s8, s8, 0x100
	s_addc_u32 s9, s9, 0
	s_cmp_gt_u32 s51, 13
	s_cbranch_scc0 .LBB0_953
	s_and_b64 vcc, exec, s[14:15]
	s_cbranch_vccz .LBB0_956
	s_barrier

.LBB0_1290:
	s_add_u32 s8, s56, 0x100
	s_addc_u32 s45, s57, 0
	s_add_u32 s6, s52, 0x40080
	v_mov_b32_e32 v8, 0
	s_addc_u32 s7, s53, 0
	s_mov_b32 s55, -2
	s_waitcnt lgkmcnt(0)
	ds_read_b128 v[0:3], v96
	ds_read_b128 v[4:7], v96 offset:1024
	ds_read_b128 v[84:87], v96 offset:2048
	ds_read_b128 v[100:103], v96 offset:3072
	s_add_u32 s26, s6, 0xfffc0080
	s_addc_u32 s27, s7, -1
	s_cmp_eq_u32 s55, 12
	s_cselect_b32 s53, s47, s27
	s_cselect_b32 s52, s46, s26
	s_cselect_b32 s27, s49, s45
	s_cselect_b32 s26, s48, s8
	v_lshl_add_u64 v[88:89], s[6:7], 0, v[82:83]
	s_add_i32 m0, s28, 0xc000
	ds_read_b128 v[104:107], v97
	ds_read_b128 v[108:111], v97 offset:1024
	ds_read_b128 v[112:115], v97 offset:2048
	ds_read_b128 v[116:119], v97 offset:3072
	ds_read_b128 v[120:123], v97 offset:4096
	ds_read_b128 v[124:127], v97 offset:5120
	ds_read_b128 v[128:131], v97 offset:6144
	ds_read_b128 v[132:135], v97 offset:7168
	global_load_lds_dwordx4 v[88:89], off
	v_lshl_add_u64 v[88:89], s[6:7], 0, v[80:81]
	s_add_i32 m0, s28, 0xe000
	s_nop 0
	global_load_lds_dwordx4 v[88:89], off
	s_waitcnt vmcnt(6) lgkmcnt(0)
	s_barrier
	v_mfma_f32_16x16x32_bf16 v[68:71], v[0:3], v[104:107], 0
	v_mfma_f32_16x16x32_bf16 v[64:67], v[84:87], v[104:107], 0
	v_mfma_f32_16x16x32_bf16 v[60:63], v[0:3], v[112:115], 0
	v_mfma_f32_16x16x32_bf16 v[56:59], v[84:87], v[112:115], 0
	v_mfma_f32_16x16x32_bf16 v[52:55], v[0:3], v[120:123], 0
	v_mfma_f32_16x16x32_bf16 v[48:51], v[84:87], v[120:123], 0
	v_mfma_f32_16x16x32_bf16 v[44:47], v[0:3], v[128:131], 0
	v_mfma_f32_16x16x32_bf16 v[40:43], v[84:87], v[128:131], 0
	v_mfma_f32_16x16x32_bf16 v[68:71], v[4:7], v[108:111], v[68:71]
	v_mfma_f32_16x16x32_bf16 v[64:67], v[100:103], v[108:111], v[64:67]
	v_mfma_f32_16x16x32_bf16 v[60:63], v[4:7], v[116:119], v[60:63]
	v_mfma_f32_16x16x32_bf16 v[56:59], v[100:103], v[116:119], v[56:59]
	v_mfma_f32_16x16x32_bf16 v[52:55], v[4:7], v[124:127], v[52:55]
	v_mfma_f32_16x16x32_bf16 v[48:51], v[100:103], v[124:127], v[48:51]
	v_mfma_f32_16x16x32_bf16 v[44:47], v[4:7], v[132:135], v[44:47]
	v_mfma_f32_16x16x32_bf16 v[40:43], v[100:103], v[132:135], v[40:43]
	s_barrier
	s_add_i32 s56, s68, s39
	v_lshl_add_u64 v[88:89], s[26:27], 0, v[74:75]
	s_mov_b32 m0, s56
	ds_read_b128 v[104:107], v97 offset:16384
	ds_read_b128 v[108:111], v97 offset:17408
	ds_read_b128 v[112:115], v97 offset:18432
	ds_read_b128 v[116:119], v97 offset:19456
	ds_read_b128 v[120:123], v97 offset:20480
	ds_read_b128 v[124:127], v97 offset:21504
	ds_read_b128 v[128:131], v97 offset:22528
	ds_read_b128 v[132:135], v97 offset:23552
	global_load_lds_dwordx4 v[88:89], off
	v_lshl_add_u64 v[136:137], s[26:27], 0, v[78:79]
	s_add_i32 m0, s56, 0x2000
	v_lshl_add_u64 v[138:139], s[52:53], 0, v[72:73]
	global_load_lds_dwordx4 v[136:137], off
	s_mov_b32 m0, s28
	v_lshl_add_u64 v[140:141], s[52:53], 0, v[76:77]
	global_load_lds_dwordx4 v[138:139], off
	s_mov_b32 m0, s29
	s_nop 0
	global_load_lds_dwordx4 v[140:141], off
	s_waitcnt vmcnt(6) lgkmcnt(0)
	s_barrier
	v_mfma_f32_16x16x32_bf16 v[36:39], v[0:3], v[104:107], 0
	v_mfma_f32_16x16x32_bf16 v[32:35], v[84:87], v[104:107], 0
	v_mfma_f32_16x16x32_bf16 v[28:31], v[0:3], v[112:115], 0
	v_mfma_f32_16x16x32_bf16 v[24:27], v[84:87], v[112:115], 0
	v_mfma_f32_16x16x32_bf16 v[20:23], v[0:3], v[120:123], 0
	v_mfma_f32_16x16x32_bf16 v[16:19], v[84:87], v[120:123], 0
	v_mfma_f32_16x16x32_bf16 v[0:3], v[0:3], v[128:131], 0
	v_mfma_f32_16x16x32_bf16 v[36:39], v[4:7], v[108:111], v[36:39]
	v_mfma_f32_16x16x32_bf16 v[32:35], v[100:103], v[108:111], v[32:35]
	v_mfma_f32_16x16x32_bf16 v[28:31], v[4:7], v[116:119], v[28:31]
	v_mfma_f32_16x16x32_bf16 v[24:27], v[100:103], v[116:119], v[24:27]
	v_mfma_f32_16x16x32_bf16 v[20:23], v[4:7], v[124:127], v[20:23]
	v_mfma_f32_16x16x32_bf16 v[16:19], v[100:103], v[124:127], v[16:19]
	v_mfma_f32_16x16x32_bf16 v[0:3], v[4:7], v[132:135], v[0:3]
	v_mfma_f32_16x16x32_bf16 v[4:7], v[84:87], v[128:131], 0
	v_mfma_f32_16x16x32_bf16 v[4:7], v[100:103], v[132:135], v[4:7]
	s_barrier
	s_add_i32 s56, 0, 0x18000
	v_add_u32_e32 v90, s56, v91
	ds_read_b128 v[8:11], v90
	ds_read_b128 v[12:15], v90 offset:1024
	ds_read_b128 v[84:87], v90 offset:2048
	ds_read_b128 v[100:103], v90 offset:3072
	s_add_u32 s26, s52, 0x40000
	s_addc_u32 s27, s53, 0
	s_mov_b32 m0, s30
	v_lshl_add_u64 v[142:143], s[26:27], 0, v[72:73]
	ds_read_b128 v[104:107], v97 offset:32768
	ds_read_b128 v[108:111], v97 offset:33792
	ds_read_b128 v[112:115], v97 offset:34816
	ds_read_b128 v[116:119], v97 offset:35840
	ds_read_b128 v[120:123], v97 offset:36864
	ds_read_b128 v[124:127], v97 offset:37888
	ds_read_b128 v[128:131], v97 offset:38912
	ds_read_b128 v[132:135], v97 offset:39936
	global_load_lds_dwordx4 v[142:143], off
	v_lshl_add_u64 v[142:143], s[26:27], 0, v[76:77]
	s_mov_b32 m0, s31
	s_nop 0
	global_load_lds_dwordx4 v[142:143], off
	s_waitcnt vmcnt(6) lgkmcnt(0)
	s_barrier
	v_mfma_f32_16x16x32_bf16 v[68:71], v[8:11], v[104:107], v[68:71]
	v_mfma_f32_16x16x32_bf16 v[64:67], v[84:87], v[104:107], v[64:67]
	v_mfma_f32_16x16x32_bf16 v[60:63], v[8:11], v[112:115], v[60:63]
	v_mfma_f32_16x16x32_bf16 v[56:59], v[84:87], v[112:115], v[56:59]
	v_mfma_f32_16x16x32_bf16 v[52:55], v[8:11], v[120:123], v[52:55]
	v_mfma_f32_16x16x32_bf16 v[48:51], v[84:87], v[120:123], v[48:51]
	v_mfma_f32_16x16x32_bf16 v[44:47], v[8:11], v[128:131], v[44:47]
	v_mfma_f32_16x16x32_bf16 v[40:43], v[84:87], v[128:131], v[40:43]
	v_mfma_f32_16x16x32_bf16 v[68:71], v[12:15], v[108:111], v[68:71]
	v_mfma_f32_16x16x32_bf16 v[64:67], v[100:103], v[108:111], v[64:67]
	v_mfma_f32_16x16x32_bf16 v[60:63], v[12:15], v[116:119], v[60:63]
	v_mfma_f32_16x16x32_bf16 v[56:59], v[100:103], v[116:119], v[56:59]
	v_mfma_f32_16x16x32_bf16 v[52:55], v[12:15], v[124:127], v[52:55]
	v_mfma_f32_16x16x32_bf16 v[48:51], v[100:103], v[124:127], v[48:51]
	v_mfma_f32_16x16x32_bf16 v[44:47], v[12:15], v[132:135], v[44:47]
	v_mfma_f32_16x16x32_bf16 v[40:43], v[100:103], v[132:135], v[40:43]
	s_barrier
	s_add_i32 s26, s56, s39
	v_lshl_add_u64 v[88:89], v[88:89], 0, s[10:11]
	s_mov_b32 m0, s26
	ds_read_b128 v[104:107], v97 offset:49152
	ds_read_b128 v[108:111], v97 offset:50176
	ds_read_b128 v[112:115], v97 offset:51200
	ds_read_b128 v[116:119], v97 offset:52224
	ds_read_b128 v[120:123], v97 offset:53248
	ds_read_b128 v[124:127], v97 offset:54272
	ds_read_b128 v[128:131], v97 offset:55296
	ds_read_b128 v[132:135], v97 offset:56320
	global_load_lds_dwordx4 v[88:89], off
	v_lshl_add_u64 v[88:89], v[136:137], 0, s[10:11]
	s_add_i32 m0, s26, 0x2000
	s_nop 0
	global_load_lds_dwordx4 v[88:89], off
	v_lshl_add_u64 v[88:89], v[138:139], 0, s[10:11]
	s_mov_b32 m0, s62
	s_nop 0
	global_load_lds_dwordx4 v[88:89], off
	v_lshl_add_u64 v[88:89], v[140:141], 0, s[10:11]
	s_mov_b32 m0, s63
	s_nop 0
	global_load_lds_dwordx4 v[88:89], off
	s_waitcnt vmcnt(6) lgkmcnt(0)
	s_barrier
	v_mfma_f32_16x16x32_bf16 v[36:39], v[8:11], v[104:107], v[36:39]
	v_mfma_f32_16x16x32_bf16 v[28:31], v[8:11], v[112:115], v[28:31]
	v_mfma_f32_16x16x32_bf16 v[20:23], v[8:11], v[120:123], v[20:23]
	v_mfma_f32_16x16x32_bf16 v[0:3], v[8:11], v[128:131], v[0:3]
	v_mfma_f32_16x16x32_bf16 v[36:39], v[12:15], v[108:111], v[36:39]
	v_mfma_f32_16x16x32_bf16 v[32:35], v[84:87], v[104:107], v[32:35]
	v_mfma_f32_16x16x32_bf16 v[28:31], v[12:15], v[116:119], v[28:31]
	v_mfma_f32_16x16x32_bf16 v[24:27], v[84:87], v[112:115], v[24:27]
	v_mfma_f32_16x16x32_bf16 v[20:23], v[12:15], v[124:127], v[20:23]
	v_mfma_f32_16x16x32_bf16 v[16:19], v[84:87], v[120:123], v[16:19]
	v_mfma_f32_16x16x32_bf16 v[12:15], v[12:15], v[132:135], v[0:3]
	v_mfma_f32_16x16x32_bf16 v[0:3], v[84:87], v[128:131], v[4:7]
	v_mfma_f32_16x16x32_bf16 v[32:35], v[100:103], v[108:111], v[32:35]
	v_mfma_f32_16x16x32_bf16 v[24:27], v[100:103], v[116:119], v[24:27]
	v_mfma_f32_16x16x32_bf16 v[16:19], v[100:103], v[124:127], v[16:19]
	v_mfma_f32_16x16x32_bf16 v[8:11], v[100:103], v[132:135], v[0:3]
	s_barrier
	s_add_i32 s55, s55, 2
	s_add_u32 s8, s8, 0x100
	s_addc_u32 s45, s45, 0
	s_add_u32 s6, s6, 0x100
	s_addc_u32 s7, s7, 0
.LBB0_1291:
	s_waitcnt lgkmcnt(0)
	ds_read_b128 v[0:3], v96
	ds_read_b128 v[4:7], v96 offset:1024
	ds_read_b128 v[84:87], v96 offset:2048
	ds_read_b128 v[100:103], v96 offset:3072
	s_add_u32 s26, s6, 0xfffc0080
	s_addc_u32 s27, s7, -1
	s_cmp_eq_u32 s55, 12
	s_cselect_b32 s53, s47, s27
	s_cselect_b32 s52, s46, s26
	s_cselect_b32 s27, s49, s45
	s_cselect_b32 s26, s48, s8
	v_lshl_add_u64 v[88:89], s[6:7], 0, v[82:83]
	s_add_i32 m0, s28, 0xc000
	ds_read_b128 v[104:107], v97
	ds_read_b128 v[108:111], v97 offset:1024
	ds_read_b128 v[112:115], v97 offset:2048
	ds_read_b128 v[116:119], v97 offset:3072
	ds_read_b128 v[120:123], v97 offset:4096
	ds_read_b128 v[124:127], v97 offset:5120
	ds_read_b128 v[128:131], v97 offset:6144
	ds_read_b128 v[132:135], v97 offset:7168
	global_load_lds_dwordx4 v[88:89], off
	v_lshl_add_u64 v[88:89], s[6:7], 0, v[80:81]
	s_add_i32 m0, s28, 0xe000
	s_nop 0
	global_load_lds_dwordx4 v[88:89], off
	s_waitcnt vmcnt(6) lgkmcnt(0)
	s_barrier
	v_mfma_f32_16x16x32_bf16 v[68:71], v[0:3], v[104:107], v[68:71]
	v_mfma_f32_16x16x32_bf16 v[64:67], v[84:87], v[104:107], v[64:67]
	v_mfma_f32_16x16x32_bf16 v[60:63], v[0:3], v[112:115], v[60:63]
	v_mfma_f32_16x16x32_bf16 v[56:59], v[84:87], v[112:115], v[56:59]
	v_mfma_f32_16x16x32_bf16 v[52:55], v[0:3], v[120:123], v[52:55]
	v_mfma_f32_16x16x32_bf16 v[48:51], v[84:87], v[120:123], v[48:51]
	v_mfma_f32_16x16x32_bf16 v[44:47], v[0:3], v[128:131], v[44:47]
	v_mfma_f32_16x16x32_bf16 v[40:43], v[84:87], v[128:131], v[40:43]
	v_mfma_f32_16x16x32_bf16 v[68:71], v[4:7], v[108:111], v[68:71]
	v_mfma_f32_16x16x32_bf16 v[64:67], v[100:103], v[108:111], v[64:67]
	v_mfma_f32_16x16x32_bf16 v[60:63], v[4:7], v[116:119], v[60:63]
	v_mfma_f32_16x16x32_bf16 v[56:59], v[100:103], v[116:119], v[56:59]
	v_mfma_f32_16x16x32_bf16 v[52:55], v[4:7], v[124:127], v[52:55]
	v_mfma_f32_16x16x32_bf16 v[48:51], v[100:103], v[124:127], v[48:51]
	v_mfma_f32_16x16x32_bf16 v[44:47], v[4:7], v[132:135], v[44:47]
	v_mfma_f32_16x16x32_bf16 v[40:43], v[100:103], v[132:135], v[40:43]
	s_barrier
	s_add_i32 s56, s68, s39
	v_lshl_add_u64 v[88:89], s[26:27], 0, v[74:75]
	s_mov_b32 m0, s56
	ds_read_b128 v[104:107], v97 offset:16384
	ds_read_b128 v[108:111], v97 offset:17408
	ds_read_b128 v[112:115], v97 offset:18432
	ds_read_b128 v[116:119], v97 offset:19456
	ds_read_b128 v[120:123], v97 offset:20480
	ds_read_b128 v[124:127], v97 offset:21504
	ds_read_b128 v[128:131], v97 offset:22528
	ds_read_b128 v[132:135], v97 offset:23552
	global_load_lds_dwordx4 v[88:89], off
	v_lshl_add_u64 v[136:137], s[26:27], 0, v[78:79]
	s_add_i32 m0, s56, 0x2000
	v_lshl_add_u64 v[138:139], s[52:53], 0, v[72:73]
	global_load_lds_dwordx4 v[136:137], off
	s_mov_b32 m0, s28
	v_lshl_add_u64 v[140:141], s[52:53], 0, v[76:77]
	global_load_lds_dwordx4 v[138:139], off
	s_mov_b32 m0, s29
	s_nop 0
	global_load_lds_dwordx4 v[140:141], off
	s_waitcnt vmcnt(6) lgkmcnt(0)
	s_barrier
	v_mfma_f32_16x16x32_bf16 v[36:39], v[0:3], v[104:107], v[36:39]
	v_mfma_f32_16x16x32_bf16 v[32:35], v[84:87], v[104:107], v[32:35]
	v_mfma_f32_16x16x32_bf16 v[28:31], v[0:3], v[112:115], v[28:31]
	v_mfma_f32_16x16x32_bf16 v[24:27], v[84:87], v[112:115], v[24:27]
	v_mfma_f32_16x16x32_bf16 v[20:23], v[0:3], v[120:123], v[20:23]
	v_mfma_f32_16x16x32_bf16 v[16:19], v[84:87], v[120:123], v[16:19]
	v_mfma_f32_16x16x32_bf16 v[0:3], v[0:3], v[128:131], v[12:15]
	v_mfma_f32_16x16x32_bf16 v[36:39], v[4:7], v[108:111], v[36:39]
	v_mfma_f32_16x16x32_bf16 v[32:35], v[100:103], v[108:111], v[32:35]
	v_mfma_f32_16x16x32_bf16 v[28:31], v[4:7], v[116:119], v[28:31]
	v_mfma_f32_16x16x32_bf16 v[24:27], v[100:103], v[116:119], v[24:27]
	v_mfma_f32_16x16x32_bf16 v[20:23], v[4:7], v[124:127], v[20:23]
	v_mfma_f32_16x16x32_bf16 v[16:19], v[100:103], v[124:127], v[16:19]
	v_mfma_f32_16x16x32_bf16 v[0:3], v[4:7], v[132:135], v[0:3]
	v_mfma_f32_16x16x32_bf16 v[4:7], v[84:87], v[128:131], v[8:11]
	v_mfma_f32_16x16x32_bf16 v[4:7], v[100:103], v[132:135], v[4:7]
	s_barrier
	s_add_i32 s56, 0, 0x18000
	v_add_u32_e32 v90, s56, v91
	ds_read_b128 v[8:11], v90
	ds_read_b128 v[12:15], v90 offset:1024
	ds_read_b128 v[84:87], v90 offset:2048
	ds_read_b128 v[100:103], v90 offset:3072
	s_add_u32 s26, s52, 0x40000
	s_addc_u32 s27, s53, 0
	s_mov_b32 m0, s30
	v_lshl_add_u64 v[142:143], s[26:27], 0, v[72:73]
	ds_read_b128 v[104:107], v97 offset:32768
	ds_read_b128 v[108:111], v97 offset:33792
	ds_read_b128 v[112:115], v97 offset:34816
	ds_read_b128 v[116:119], v97 offset:35840
	ds_read_b128 v[120:123], v97 offset:36864
	ds_read_b128 v[124:127], v97 offset:37888
	ds_read_b128 v[128:131], v97 offset:38912
	ds_read_b128 v[132:135], v97 offset:39936
	global_load_lds_dwordx4 v[142:143], off
	v_lshl_add_u64 v[142:143], s[26:27], 0, v[76:77]
	s_mov_b32 m0, s31
	s_nop 0
	global_load_lds_dwordx4 v[142:143], off
	s_waitcnt vmcnt(6) lgkmcnt(0)
	s_barrier
	v_mfma_f32_16x16x32_bf16 v[68:71], v[8:11], v[104:107], v[68:71]
	v_mfma_f32_16x16x32_bf16 v[64:67], v[84:87], v[104:107], v[64:67]
	v_mfma_f32_16x16x32_bf16 v[60:63], v[8:11], v[112:115], v[60:63]
	v_mfma_f32_16x16x32_bf16 v[56:59], v[84:87], v[112:115], v[56:59]
	v_mfma_f32_16x16x32_bf16 v[52:55], v[8:11], v[120:123], v[52:55]
	v_mfma_f32_16x16x32_bf16 v[48:51], v[84:87], v[120:123], v[48:51]
	v_mfma_f32_16x16x32_bf16 v[44:47], v[8:11], v[128:131], v[44:47]
	v_mfma_f32_16x16x32_bf16 v[40:43], v[84:87], v[128:131], v[40:43]
	v_mfma_f32_16x16x32_bf16 v[68:71], v[12:15], v[108:111], v[68:71]
	v_mfma_f32_16x16x32_bf16 v[64:67], v[100:103], v[108:111], v[64:67]
	v_mfma_f32_16x16x32_bf16 v[60:63], v[12:15], v[116:119], v[60:63]
	v_mfma_f32_16x16x32_bf16 v[56:59], v[100:103], v[116:119], v[56:59]
	v_mfma_f32_16x16x32_bf16 v[52:55], v[12:15], v[124:127], v[52:55]
	v_mfma_f32_16x16x32_bf16 v[48:51], v[100:103], v[124:127], v[48:51]
	v_mfma_f32_16x16x32_bf16 v[44:47], v[12:15], v[132:135], v[44:47]
	v_mfma_f32_16x16x32_bf16 v[40:43], v[100:103], v[132:135], v[40:43]
	s_barrier
	s_add_i32 s26, s56, s39
	v_lshl_add_u64 v[88:89], v[88:89], 0, s[10:11]
	s_mov_b32 m0, s26
	ds_read_b128 v[104:107], v97 offset:49152
	ds_read_b128 v[108:111], v97 offset:50176
	ds_read_b128 v[112:115], v97 offset:51200
	ds_read_b128 v[116:119], v97 offset:52224
	ds_read_b128 v[120:123], v97 offset:53248
	ds_read_b128 v[124:127], v97 offset:54272
	ds_read_b128 v[128:131], v97 offset:55296
	ds_read_b128 v[132:135], v97 offset:56320
	global_load_lds_dwordx4 v[88:89], off
	v_lshl_add_u64 v[88:89], v[136:137], 0, s[10:11]
	s_add_i32 m0, s26, 0x2000
	s_nop 0
	global_load_lds_dwordx4 v[88:89], off
	v_lshl_add_u64 v[88:89], v[138:139], 0, s[10:11]
	s_mov_b32 m0, s62
	s_nop 0
	global_load_lds_dwordx4 v[88:89], off
	v_lshl_add_u64 v[88:89], v[140:141], 0, s[10:11]
	s_mov_b32 m0, s63
	s_nop 0
	global_load_lds_dwordx4 v[88:89], off
	s_waitcnt vmcnt(6) lgkmcnt(0)
	s_barrier
	v_mfma_f32_16x16x32_bf16 v[36:39], v[8:11], v[104:107], v[36:39]
	v_mfma_f32_16x16x32_bf16 v[28:31], v[8:11], v[112:115], v[28:31]
	v_mfma_f32_16x16x32_bf16 v[20:23], v[8:11], v[120:123], v[20:23]
	v_mfma_f32_16x16x32_bf16 v[0:3], v[8:11], v[128:131], v[0:3]
	v_mfma_f32_16x16x32_bf16 v[36:39], v[12:15], v[108:111], v[36:39]
	v_mfma_f32_16x16x32_bf16 v[32:35], v[84:87], v[104:107], v[32:35]
	v_mfma_f32_16x16x32_bf16 v[28:31], v[12:15], v[116:119], v[28:31]
	v_mfma_f32_16x16x32_bf16 v[24:27], v[84:87], v[112:115], v[24:27]
	v_mfma_f32_16x16x32_bf16 v[20:23], v[12:15], v[124:127], v[20:23]
	v_mfma_f32_16x16x32_bf16 v[16:19], v[84:87], v[120:123], v[16:19]
	v_mfma_f32_16x16x32_bf16 v[12:15], v[12:15], v[132:135], v[0:3]
	v_mfma_f32_16x16x32_bf16 v[0:3], v[84:87], v[128:131], v[4:7]
	v_mfma_f32_16x16x32_bf16 v[32:35], v[100:103], v[108:111], v[32:35]
	v_mfma_f32_16x16x32_bf16 v[24:27], v[100:103], v[116:119], v[24:27]
	v_mfma_f32_16x16x32_bf16 v[16:19], v[100:103], v[124:127], v[16:19]
	v_mfma_f32_16x16x32_bf16 v[8:11], v[100:103], v[132:135], v[0:3]
	s_barrier
	s_add_i32 s55, s55, 2
	s_add_u32 s8, s8, 0x100
	s_addc_u32 s45, s45, 0
	s_add_u32 s6, s6, 0x100
	s_addc_u32 s7, s7, 0
	s_cmp_gt_u32 s55, 13
	s_cbranch_scc0 .LBB0_1291
	s_and_b64 vcc, exec, s[14:15]
	s_cbranch_vccz .LBB0_1294
	s_barrier

.LBB0_1518:
	s_add_u32 s23, s6, 0x100
	s_addc_u32 s60, s7, 0
	s_add_u32 s4, s4, 0x40080
	v_mov_b32_e32 v0, 0
	s_addc_u32 s5, s5, 0
	s_mov_b32 s61, -2
	ds_read_b128 v[128:131], v246
	ds_read_b128 v[132:135], v246 offset:1024
	ds_read_b128 v[136:139], v246 offset:2048
	ds_read_b128 v[140:143], v246 offset:3072
	ds_read_b128 v[144:147], v247
	ds_read_b128 v[148:151], v247 offset:1024
	ds_read_b128 v[152:155], v247 offset:2048
	ds_read_b128 v[156:159], v247 offset:3072
	s_add_u32 s6, s4, 0xfffc0080
	s_addc_u32 s7, s5, -1
	s_cmp_eq_u32 s61, 12
	s_cselect_b32 s35, s25, s7
	s_cselect_b32 s34, s24, s6
	s_cselect_b32 s7, s27, s60
	s_cselect_b32 s6, s26, s23
	v_lshl_add_u64 v[192:193], s[4:5], 0, v[218:219]
	s_add_i32 m0, s36, 0xc000
	ds_read_b128 v[160:163], v248
	ds_read_b128 v[164:167], v248 offset:1024
	ds_read_b128 v[168:171], v248 offset:2048
	ds_read_b128 v[172:175], v248 offset:3072
	ds_read_b128 v[176:179], v248 offset:4096
	ds_read_b128 v[180:183], v248 offset:5120
	ds_read_b128 v[184:187], v248 offset:6144
	ds_read_b128 v[188:191], v248 offset:7168
	global_load_lds_dwordx4 v[192:193], off
	v_lshl_add_u64 v[192:193], s[4:5], 0, v[216:217]
	s_add_i32 m0, s36, 0xe000
	s_nop 0
	global_load_lds_dwordx4 v[192:193], off
	s_waitcnt vmcnt(8) lgkmcnt(0)
	s_barrier
	v_mfma_f32_16x16x32_bf16 v[124:127], v[128:131], v[160:163], 0
	v_mfma_f32_16x16x32_bf16 v[120:123], v[136:139], v[160:163], 0
	v_mfma_f32_16x16x32_bf16 v[112:115], v[128:131], v[168:171], 0
	v_mfma_f32_16x16x32_bf16 v[104:107], v[136:139], v[168:171], 0
	v_mfma_f32_16x16x32_bf16 v[96:99], v[128:131], v[176:179], 0
	v_mfma_f32_16x16x32_bf16 v[88:91], v[136:139], v[176:179], 0
	v_mfma_f32_16x16x32_bf16 v[80:83], v[128:131], v[184:187], 0
	v_mfma_f32_16x16x32_bf16 v[72:75], v[136:139], v[184:187], 0
	v_mfma_f32_16x16x32_bf16 v[124:127], v[132:135], v[164:167], v[124:127]
	v_mfma_f32_16x16x32_bf16 v[120:123], v[140:143], v[164:167], v[120:123]
	v_mfma_f32_16x16x32_bf16 v[112:115], v[132:135], v[172:175], v[112:115]
	v_mfma_f32_16x16x32_bf16 v[104:107], v[140:143], v[172:175], v[104:107]
	v_mfma_f32_16x16x32_bf16 v[96:99], v[132:135], v[180:183], v[96:99]
	v_mfma_f32_16x16x32_bf16 v[88:91], v[140:143], v[180:183], v[88:91]
	v_mfma_f32_16x16x32_bf16 v[80:83], v[132:135], v[188:191], v[80:83]
	v_mfma_f32_16x16x32_bf16 v[72:75], v[140:143], v[188:191], v[72:75]
	v_mfma_f32_16x16x32_bf16 v[116:119], v[144:147], v[160:163], 0
	v_mfma_f32_16x16x32_bf16 v[108:111], v[152:155], v[160:163], 0
	v_mfma_f32_16x16x32_bf16 v[100:103], v[144:147], v[168:171], 0
	v_mfma_f32_16x16x32_bf16 v[92:95], v[152:155], v[168:171], 0
	v_mfma_f32_16x16x32_bf16 v[84:87], v[144:147], v[176:179], 0
	v_mfma_f32_16x16x32_bf16 v[76:79], v[152:155], v[176:179], 0
	v_mfma_f32_16x16x32_bf16 v[68:71], v[144:147], v[184:187], 0
	v_mfma_f32_16x16x32_bf16 v[64:67], v[152:155], v[184:187], 0
	v_mfma_f32_16x16x32_bf16 v[116:119], v[148:151], v[164:167], v[116:119]
	v_mfma_f32_16x16x32_bf16 v[108:111], v[156:159], v[164:167], v[108:111]
	v_mfma_f32_16x16x32_bf16 v[100:103], v[148:151], v[172:175], v[100:103]
	v_mfma_f32_16x16x32_bf16 v[92:95], v[156:159], v[172:175], v[92:95]
	v_mfma_f32_16x16x32_bf16 v[84:87], v[148:151], v[180:183], v[84:87]
	v_mfma_f32_16x16x32_bf16 v[76:79], v[156:159], v[180:183], v[76:79]
	v_mfma_f32_16x16x32_bf16 v[68:71], v[148:151], v[188:191], v[68:71]
	v_mfma_f32_16x16x32_bf16 v[64:67], v[156:159], v[188:191], v[64:67]
	s_barrier
	s_add_i32 s62, s48, s3
	v_lshl_add_u64 v[192:193], s[6:7], 0, v[212:213]
	s_mov_b32 m0, s62
	ds_read_b128 v[160:163], v248 offset:16384
	ds_read_b128 v[164:167], v248 offset:17408
	ds_read_b128 v[168:171], v248 offset:18432
	ds_read_b128 v[172:175], v248 offset:19456
	ds_read_b128 v[176:179], v248 offset:20480
	ds_read_b128 v[180:183], v248 offset:21504
	ds_read_b128 v[184:187], v248 offset:22528
	ds_read_b128 v[188:191], v248 offset:23552
	global_load_lds_dwordx4 v[192:193], off
	s_add_i32 m0, s62, 0x2000
	s_add_u32 s62, s6, 0x40000
	v_lshl_add_u64 v[194:195], s[6:7], 0, v[208:209]
	s_addc_u32 s63, s7, 0
	s_add_i32 s64, s49, s3
	global_load_lds_dwordx4 v[194:195], off
	v_lshl_add_u64 v[196:197], s[62:63], 0, v[212:213]
	s_mov_b32 m0, s64
	v_lshl_add_u64 v[198:199], s[34:35], 0, v[210:211]
	global_load_lds_dwordx4 v[196:197], off
	v_lshl_add_u64 v[196:197], s[62:63], 0, v[208:209]
	s_add_i32 m0, s64, 0x2000
	s_nop 0
	global_load_lds_dwordx4 v[196:197], off
	v_lshl_add_u64 v[196:197], s[34:35], 0, v[214:215]
	s_mov_b32 m0, s36
	s_nop 0
	global_load_lds_dwordx4 v[196:197], off
	s_mov_b32 m0, s37
	s_nop 0
	global_load_lds_dwordx4 v[198:199], off
	s_waitcnt vmcnt(8) lgkmcnt(0)
	s_barrier
	v_mfma_f32_16x16x32_bf16 v[60:63], v[128:131], v[160:163], 0
	v_mfma_f32_16x16x32_bf16 v[56:59], v[136:139], v[160:163], 0
	v_mfma_f32_16x16x32_bf16 v[48:51], v[128:131], v[168:171], 0
	v_mfma_f32_16x16x32_bf16 v[40:43], v[136:139], v[168:171], 0
	v_mfma_f32_16x16x32_bf16 v[32:35], v[128:131], v[176:179], 0
	v_mfma_f32_16x16x32_bf16 v[24:27], v[136:139], v[176:179], 0
	v_mfma_f32_16x16x32_bf16 v[16:19], v[128:131], v[184:187], 0
	v_mfma_f32_16x16x32_bf16 v[8:11], v[136:139], v[184:187], 0
	v_mfma_f32_16x16x32_bf16 v[60:63], v[132:135], v[164:167], v[60:63]
	v_mfma_f32_16x16x32_bf16 v[56:59], v[140:143], v[164:167], v[56:59]
	v_mfma_f32_16x16x32_bf16 v[48:51], v[132:135], v[172:175], v[48:51]
	v_mfma_f32_16x16x32_bf16 v[40:43], v[140:143], v[172:175], v[40:43]
	v_mfma_f32_16x16x32_bf16 v[32:35], v[132:135], v[180:183], v[32:35]
	v_mfma_f32_16x16x32_bf16 v[24:27], v[140:143], v[180:183], v[24:27]
	v_mfma_f32_16x16x32_bf16 v[16:19], v[132:135], v[188:191], v[16:19]
	v_mfma_f32_16x16x32_bf16 v[8:11], v[140:143], v[188:191], v[8:11]
	v_mfma_f32_16x16x32_bf16 v[52:55], v[144:147], v[160:163], 0
	v_mfma_f32_16x16x32_bf16 v[44:47], v[152:155], v[160:163], 0
	v_mfma_f32_16x16x32_bf16 v[36:39], v[144:147], v[168:171], 0
	v_mfma_f32_16x16x32_bf16 v[28:31], v[152:155], v[168:171], 0
	v_mfma_f32_16x16x32_bf16 v[20:23], v[144:147], v[176:179], 0
	v_mfma_f32_16x16x32_bf16 v[12:15], v[152:155], v[176:179], 0
	v_mfma_f32_16x16x32_bf16 v[4:7], v[144:147], v[184:187], 0
	v_mfma_f32_16x16x32_bf16 v[0:3], v[152:155], v[184:187], 0
	v_mfma_f32_16x16x32_bf16 v[52:55], v[148:151], v[164:167], v[52:55]
	v_mfma_f32_16x16x32_bf16 v[44:47], v[156:159], v[164:167], v[44:47]
	v_mfma_f32_16x16x32_bf16 v[36:39], v[148:151], v[172:175], v[36:39]
	v_mfma_f32_16x16x32_bf16 v[28:31], v[156:159], v[172:175], v[28:31]
	v_mfma_f32_16x16x32_bf16 v[20:23], v[148:151], v[180:183], v[20:23]
	v_mfma_f32_16x16x32_bf16 v[12:15], v[156:159], v[180:183], v[12:15]
	v_mfma_f32_16x16x32_bf16 v[4:7], v[148:151], v[188:191], v[4:7]
	v_mfma_f32_16x16x32_bf16 v[0:3], v[156:159], v[188:191], v[0:3]
	s_barrier
	s_add_i32 s62, 0, 0x18000
	s_add_i32 s63, 0, 0x1c000
	v_add_u32_e32 v140, s62, v245
	v_add_u32_e32 v156, s63, v245
	ds_read_b128 v[128:131], v140
	ds_read_b128 v[132:135], v140 offset:1024
	ds_read_b128 v[136:139], v140 offset:2048
	ds_read_b128 v[140:143], v140 offset:3072
	ds_read_b128 v[144:147], v156
	ds_read_b128 v[148:151], v156 offset:1024
	ds_read_b128 v[152:155], v156 offset:2048
	ds_read_b128 v[156:159], v156 offset:3072
	s_add_u32 s34, s34, 0x40000
	s_addc_u32 s35, s35, 0
	s_mov_b32 m0, s38
	v_lshl_add_u64 v[200:201], s[34:35], 0, v[214:215]
	ds_read_b128 v[160:163], v248 offset:32768
	ds_read_b128 v[164:167], v248 offset:33792
	ds_read_b128 v[168:171], v248 offset:34816
	ds_read_b128 v[172:175], v248 offset:35840
	ds_read_b128 v[176:179], v248 offset:36864
	ds_read_b128 v[180:183], v248 offset:37888
	ds_read_b128 v[184:187], v248 offset:38912
	ds_read_b128 v[188:191], v248 offset:39936
	global_load_lds_dwordx4 v[200:201], off
	v_lshl_add_u64 v[200:201], s[34:35], 0, v[210:211]
	s_mov_b32 m0, s39
	s_nop 0
	global_load_lds_dwordx4 v[200:201], off
	s_waitcnt vmcnt(8) lgkmcnt(0)
	s_barrier
	v_mfma_f32_16x16x32_bf16 v[124:127], v[128:131], v[160:163], v[124:127]
	v_mfma_f32_16x16x32_bf16 v[120:123], v[136:139], v[160:163], v[120:123]
	v_mfma_f32_16x16x32_bf16 v[112:115], v[128:131], v[168:171], v[112:115]
	v_mfma_f32_16x16x32_bf16 v[104:107], v[136:139], v[168:171], v[104:107]
	v_mfma_f32_16x16x32_bf16 v[96:99], v[128:131], v[176:179], v[96:99]
	v_mfma_f32_16x16x32_bf16 v[88:91], v[136:139], v[176:179], v[88:91]
	v_mfma_f32_16x16x32_bf16 v[80:83], v[128:131], v[184:187], v[80:83]
	v_mfma_f32_16x16x32_bf16 v[72:75], v[136:139], v[184:187], v[72:75]
	v_mfma_f32_16x16x32_bf16 v[124:127], v[132:135], v[164:167], v[124:127]
	v_mfma_f32_16x16x32_bf16 v[120:123], v[140:143], v[164:167], v[120:123]
	v_mfma_f32_16x16x32_bf16 v[112:115], v[132:135], v[172:175], v[112:115]
	v_mfma_f32_16x16x32_bf16 v[104:107], v[140:143], v[172:175], v[104:107]
	v_mfma_f32_16x16x32_bf16 v[96:99], v[132:135], v[180:183], v[96:99]
	v_mfma_f32_16x16x32_bf16 v[88:91], v[140:143], v[180:183], v[88:91]
	v_mfma_f32_16x16x32_bf16 v[80:83], v[132:135], v[188:191], v[80:83]
	v_mfma_f32_16x16x32_bf16 v[72:75], v[140:143], v[188:191], v[72:75]
	v_mfma_f32_16x16x32_bf16 v[116:119], v[144:147], v[160:163], v[116:119]
	v_mfma_f32_16x16x32_bf16 v[108:111], v[152:155], v[160:163], v[108:111]
	v_mfma_f32_16x16x32_bf16 v[100:103], v[144:147], v[168:171], v[100:103]
	v_mfma_f32_16x16x32_bf16 v[92:95], v[152:155], v[168:171], v[92:95]
	v_mfma_f32_16x16x32_bf16 v[84:87], v[144:147], v[176:179], v[84:87]
	v_mfma_f32_16x16x32_bf16 v[76:79], v[152:155], v[176:179], v[76:79]
	v_mfma_f32_16x16x32_bf16 v[68:71], v[144:147], v[184:187], v[68:71]
	v_mfma_f32_16x16x32_bf16 v[64:67], v[152:155], v[184:187], v[64:67]
	v_mfma_f32_16x16x32_bf16 v[116:119], v[148:151], v[164:167], v[116:119]
	v_mfma_f32_16x16x32_bf16 v[108:111], v[156:159], v[164:167], v[108:111]
	v_mfma_f32_16x16x32_bf16 v[100:103], v[148:151], v[172:175], v[100:103]
	v_mfma_f32_16x16x32_bf16 v[92:95], v[156:159], v[172:175], v[92:95]
	v_mfma_f32_16x16x32_bf16 v[84:87], v[148:151], v[180:183], v[84:87]
	v_mfma_f32_16x16x32_bf16 v[76:79], v[156:159], v[180:183], v[76:79]
	v_mfma_f32_16x16x32_bf16 v[68:71], v[148:151], v[188:191], v[68:71]
	v_mfma_f32_16x16x32_bf16 v[64:67], v[156:159], v[188:191], v[64:67]
	s_barrier
	s_add_i32 s34, s62, s3
	v_lshl_add_u64 v[192:193], v[192:193], 0, s[10:11]
	s_mov_b32 m0, s34
	ds_read_b128 v[160:163], v248 offset:49152
	ds_read_b128 v[164:167], v248 offset:50176
	ds_read_b128 v[168:171], v248 offset:51200
	ds_read_b128 v[172:175], v248 offset:52224
	ds_read_b128 v[176:179], v248 offset:53248
	ds_read_b128 v[180:183], v248 offset:54272
	ds_read_b128 v[184:187], v248 offset:55296
	ds_read_b128 v[188:191], v248 offset:56320
	global_load_lds_dwordx4 v[192:193], off
	s_add_i32 m0, s34, 0x2000
	s_add_u32 s6, s6, 0x40080
	v_lshl_add_u64 v[192:193], v[194:195], 0, s[10:11]
	s_addc_u32 s7, s7, 0
	s_add_i32 s34, s63, s3
	global_load_lds_dwordx4 v[192:193], off
	v_lshl_add_u64 v[192:193], s[6:7], 0, v[212:213]
	s_mov_b32 m0, s34
	s_nop 0
	global_load_lds_dwordx4 v[192:193], off
	v_lshl_add_u64 v[192:193], s[6:7], 0, v[208:209]
	s_add_i32 m0, s34, 0x2000
	s_nop 0
	global_load_lds_dwordx4 v[192:193], off
	v_lshl_add_u64 v[192:193], v[196:197], 0, s[10:11]
	s_mov_b32 m0, s44
	s_nop 0
	global_load_lds_dwordx4 v[192:193], off
	v_lshl_add_u64 v[192:193], v[198:199], 0, s[10:11]
	s_mov_b32 m0, s45
	s_nop 0
	global_load_lds_dwordx4 v[192:193], off
	s_waitcnt vmcnt(8) lgkmcnt(0)
	s_barrier
	v_mfma_f32_16x16x32_bf16 v[60:63], v[128:131], v[160:163], v[60:63]
	v_mfma_f32_16x16x32_bf16 v[56:59], v[136:139], v[160:163], v[56:59]
	v_mfma_f32_16x16x32_bf16 v[48:51], v[128:131], v[168:171], v[48:51]
	v_mfma_f32_16x16x32_bf16 v[40:43], v[136:139], v[168:171], v[40:43]
	v_mfma_f32_16x16x32_bf16 v[32:35], v[128:131], v[176:179], v[32:35]
	v_mfma_f32_16x16x32_bf16 v[24:27], v[136:139], v[176:179], v[24:27]
	v_mfma_f32_16x16x32_bf16 v[16:19], v[128:131], v[184:187], v[16:19]
	v_mfma_f32_16x16x32_bf16 v[8:11], v[136:139], v[184:187], v[8:11]
	v_mfma_f32_16x16x32_bf16 v[60:63], v[132:135], v[164:167], v[60:63]
	v_mfma_f32_16x16x32_bf16 v[56:59], v[140:143], v[164:167], v[56:59]
	v_mfma_f32_16x16x32_bf16 v[48:51], v[132:135], v[172:175], v[48:51]
	v_mfma_f32_16x16x32_bf16 v[40:43], v[140:143], v[172:175], v[40:43]
	v_mfma_f32_16x16x32_bf16 v[32:35], v[132:135], v[180:183], v[32:35]
	v_mfma_f32_16x16x32_bf16 v[24:27], v[140:143], v[180:183], v[24:27]
	v_mfma_f32_16x16x32_bf16 v[16:19], v[132:135], v[188:191], v[16:19]
	v_mfma_f32_16x16x32_bf16 v[8:11], v[140:143], v[188:191], v[8:11]
	v_mfma_f32_16x16x32_bf16 v[52:55], v[144:147], v[160:163], v[52:55]
	v_mfma_f32_16x16x32_bf16 v[44:47], v[152:155], v[160:163], v[44:47]
	v_mfma_f32_16x16x32_bf16 v[36:39], v[144:147], v[168:171], v[36:39]
	v_mfma_f32_16x16x32_bf16 v[28:31], v[152:155], v[168:171], v[28:31]
	v_mfma_f32_16x16x32_bf16 v[20:23], v[144:147], v[176:179], v[20:23]
	v_mfma_f32_16x16x32_bf16 v[12:15], v[152:155], v[176:179], v[12:15]
	v_mfma_f32_16x16x32_bf16 v[4:7], v[144:147], v[184:187], v[4:7]
	v_mfma_f32_16x16x32_bf16 v[0:3], v[152:155], v[184:187], v[0:3]
	v_mfma_f32_16x16x32_bf16 v[52:55], v[148:151], v[164:167], v[52:55]
	v_mfma_f32_16x16x32_bf16 v[44:47], v[156:159], v[164:167], v[44:47]
	v_mfma_f32_16x16x32_bf16 v[36:39], v[148:151], v[172:175], v[36:39]
	v_mfma_f32_16x16x32_bf16 v[28:31], v[156:159], v[172:175], v[28:31]
	v_mfma_f32_16x16x32_bf16 v[20:23], v[148:151], v[180:183], v[20:23]
	v_mfma_f32_16x16x32_bf16 v[12:15], v[156:159], v[180:183], v[12:15]
	v_mfma_f32_16x16x32_bf16 v[4:7], v[148:151], v[188:191], v[4:7]
	v_mfma_f32_16x16x32_bf16 v[0:3], v[156:159], v[188:191], v[0:3]
	s_barrier
	s_add_i32 s61, s61, 2
	s_add_u32 s23, s23, 0x100
	s_addc_u32 s60, s60, 0
	s_add_u32 s4, s4, 0x100
	s_addc_u32 s5, s5, 0
.LBB0_1519:
	ds_read_b128 v[128:131], v246
	ds_read_b128 v[132:135], v246 offset:1024
	ds_read_b128 v[136:139], v246 offset:2048
	ds_read_b128 v[140:143], v246 offset:3072
	ds_read_b128 v[144:147], v247
	ds_read_b128 v[148:151], v247 offset:1024
	ds_read_b128 v[152:155], v247 offset:2048
	ds_read_b128 v[156:159], v247 offset:3072
	s_add_u32 s6, s4, 0xfffc0080
	s_addc_u32 s7, s5, -1
	s_cmp_eq_u32 s61, 12
	s_cselect_b32 s35, s25, s7
	s_cselect_b32 s34, s24, s6
	s_cselect_b32 s7, s27, s60
	s_cselect_b32 s6, s26, s23
	v_lshl_add_u64 v[192:193], s[4:5], 0, v[218:219]
	s_add_i32 m0, s36, 0xc000
	ds_read_b128 v[160:163], v248
	ds_read_b128 v[164:167], v248 offset:1024
	ds_read_b128 v[168:171], v248 offset:2048
	ds_read_b128 v[172:175], v248 offset:3072
	ds_read_b128 v[176:179], v248 offset:4096
	ds_read_b128 v[180:183], v248 offset:5120
	ds_read_b128 v[184:187], v248 offset:6144
	ds_read_b128 v[188:191], v248 offset:7168
	global_load_lds_dwordx4 v[192:193], off
	v_lshl_add_u64 v[192:193], s[4:5], 0, v[216:217]
	s_add_i32 m0, s36, 0xe000
	s_nop 0
	global_load_lds_dwordx4 v[192:193], off
	s_waitcnt vmcnt(8) lgkmcnt(0)
	s_barrier
	v_mfma_f32_16x16x32_bf16 v[124:127], v[128:131], v[160:163], v[124:127]
	v_mfma_f32_16x16x32_bf16 v[120:123], v[136:139], v[160:163], v[120:123]
	v_mfma_f32_16x16x32_bf16 v[112:115], v[128:131], v[168:171], v[112:115]
	v_mfma_f32_16x16x32_bf16 v[104:107], v[136:139], v[168:171], v[104:107]
	v_mfma_f32_16x16x32_bf16 v[96:99], v[128:131], v[176:179], v[96:99]
	v_mfma_f32_16x16x32_bf16 v[88:91], v[136:139], v[176:179], v[88:91]
	v_mfma_f32_16x16x32_bf16 v[80:83], v[128:131], v[184:187], v[80:83]
	v_mfma_f32_16x16x32_bf16 v[72:75], v[136:139], v[184:187], v[72:75]
	v_mfma_f32_16x16x32_bf16 v[124:127], v[132:135], v[164:167], v[124:127]
	v_mfma_f32_16x16x32_bf16 v[120:123], v[140:143], v[164:167], v[120:123]
	v_mfma_f32_16x16x32_bf16 v[112:115], v[132:135], v[172:175], v[112:115]
	v_mfma_f32_16x16x32_bf16 v[104:107], v[140:143], v[172:175], v[104:107]
	v_mfma_f32_16x16x32_bf16 v[96:99], v[132:135], v[180:183], v[96:99]
	v_mfma_f32_16x16x32_bf16 v[88:91], v[140:143], v[180:183], v[88:91]
	v_mfma_f32_16x16x32_bf16 v[80:83], v[132:135], v[188:191], v[80:83]
	v_mfma_f32_16x16x32_bf16 v[72:75], v[140:143], v[188:191], v[72:75]
	v_mfma_f32_16x16x32_bf16 v[116:119], v[144:147], v[160:163], v[116:119]
	v_mfma_f32_16x16x32_bf16 v[108:111], v[152:155], v[160:163], v[108:111]
	v_mfma_f32_16x16x32_bf16 v[100:103], v[144:147], v[168:171], v[100:103]
	v_mfma_f32_16x16x32_bf16 v[92:95], v[152:155], v[168:171], v[92:95]
	v_mfma_f32_16x16x32_bf16 v[84:87], v[144:147], v[176:179], v[84:87]
	v_mfma_f32_16x16x32_bf16 v[76:79], v[152:155], v[176:179], v[76:79]
	v_mfma_f32_16x16x32_bf16 v[68:71], v[144:147], v[184:187], v[68:71]
	v_mfma_f32_16x16x32_bf16 v[64:67], v[152:155], v[184:187], v[64:67]
	v_mfma_f32_16x16x32_bf16 v[116:119], v[148:151], v[164:167], v[116:119]
	v_mfma_f32_16x16x32_bf16 v[108:111], v[156:159], v[164:167], v[108:111]
	v_mfma_f32_16x16x32_bf16 v[100:103], v[148:151], v[172:175], v[100:103]
	v_mfma_f32_16x16x32_bf16 v[92:95], v[156:159], v[172:175], v[92:95]
	v_mfma_f32_16x16x32_bf16 v[84:87], v[148:151], v[180:183], v[84:87]
	v_mfma_f32_16x16x32_bf16 v[76:79], v[156:159], v[180:183], v[76:79]
	v_mfma_f32_16x16x32_bf16 v[68:71], v[148:151], v[188:191], v[68:71]
	v_mfma_f32_16x16x32_bf16 v[64:67], v[156:159], v[188:191], v[64:67]
	s_barrier
	s_add_i32 s62, s48, s3
	v_lshl_add_u64 v[192:193], s[6:7], 0, v[212:213]
	s_mov_b32 m0, s62
	ds_read_b128 v[160:163], v248 offset:16384
	ds_read_b128 v[164:167], v248 offset:17408
	ds_read_b128 v[168:171], v248 offset:18432
	ds_read_b128 v[172:175], v248 offset:19456
	ds_read_b128 v[176:179], v248 offset:20480
	ds_read_b128 v[180:183], v248 offset:21504
	ds_read_b128 v[184:187], v248 offset:22528
	ds_read_b128 v[188:191], v248 offset:23552
	global_load_lds_dwordx4 v[192:193], off
	s_add_i32 m0, s62, 0x2000
	s_add_u32 s62, s6, 0x40000
	v_lshl_add_u64 v[194:195], s[6:7], 0, v[208:209]
	s_addc_u32 s63, s7, 0
	s_add_i32 s64, s49, s3
	global_load_lds_dwordx4 v[194:195], off
	v_lshl_add_u64 v[196:197], s[62:63], 0, v[212:213]
	s_mov_b32 m0, s64
	v_lshl_add_u64 v[198:199], s[34:35], 0, v[210:211]
	global_load_lds_dwordx4 v[196:197], off
	v_lshl_add_u64 v[196:197], s[62:63], 0, v[208:209]
	s_add_i32 m0, s64, 0x2000
	s_nop 0
	global_load_lds_dwordx4 v[196:197], off
	v_lshl_add_u64 v[196:197], s[34:35], 0, v[214:215]
	s_mov_b32 m0, s36
	s_nop 0
	global_load_lds_dwordx4 v[196:197], off
	s_mov_b32 m0, s37
	s_nop 0
	global_load_lds_dwordx4 v[198:199], off
	s_waitcnt vmcnt(8) lgkmcnt(0)
	s_barrier
	v_mfma_f32_16x16x32_bf16 v[60:63], v[128:131], v[160:163], v[60:63]
	v_mfma_f32_16x16x32_bf16 v[56:59], v[136:139], v[160:163], v[56:59]
	v_mfma_f32_16x16x32_bf16 v[48:51], v[128:131], v[168:171], v[48:51]
	v_mfma_f32_16x16x32_bf16 v[40:43], v[136:139], v[168:171], v[40:43]
	v_mfma_f32_16x16x32_bf16 v[32:35], v[128:131], v[176:179], v[32:35]
	v_mfma_f32_16x16x32_bf16 v[24:27], v[136:139], v[176:179], v[24:27]
	v_mfma_f32_16x16x32_bf16 v[16:19], v[128:131], v[184:187], v[16:19]
	v_mfma_f32_16x16x32_bf16 v[8:11], v[136:139], v[184:187], v[8:11]
	v_mfma_f32_16x16x32_bf16 v[60:63], v[132:135], v[164:167], v[60:63]
	v_mfma_f32_16x16x32_bf16 v[56:59], v[140:143], v[164:167], v[56:59]
	v_mfma_f32_16x16x32_bf16 v[48:51], v[132:135], v[172:175], v[48:51]
	v_mfma_f32_16x16x32_bf16 v[40:43], v[140:143], v[172:175], v[40:43]
	v_mfma_f32_16x16x32_bf16 v[32:35], v[132:135], v[180:183], v[32:35]
	v_mfma_f32_16x16x32_bf16 v[24:27], v[140:143], v[180:183], v[24:27]
	v_mfma_f32_16x16x32_bf16 v[16:19], v[132:135], v[188:191], v[16:19]
	v_mfma_f32_16x16x32_bf16 v[8:11], v[140:143], v[188:191], v[8:11]
	v_mfma_f32_16x16x32_bf16 v[52:55], v[144:147], v[160:163], v[52:55]
	v_mfma_f32_16x16x32_bf16 v[44:47], v[152:155], v[160:163], v[44:47]
	v_mfma_f32_16x16x32_bf16 v[36:39], v[144:147], v[168:171], v[36:39]
	v_mfma_f32_16x16x32_bf16 v[28:31], v[152:155], v[168:171], v[28:31]
	v_mfma_f32_16x16x32_bf16 v[20:23], v[144:147], v[176:179], v[20:23]
	v_mfma_f32_16x16x32_bf16 v[12:15], v[152:155], v[176:179], v[12:15]
	v_mfma_f32_16x16x32_bf16 v[4:7], v[144:147], v[184:187], v[4:7]
	v_mfma_f32_16x16x32_bf16 v[0:3], v[152:155], v[184:187], v[0:3]
	v_mfma_f32_16x16x32_bf16 v[52:55], v[148:151], v[164:167], v[52:55]
	v_mfma_f32_16x16x32_bf16 v[44:47], v[156:159], v[164:167], v[44:47]
	v_mfma_f32_16x16x32_bf16 v[36:39], v[148:151], v[172:175], v[36:39]
	v_mfma_f32_16x16x32_bf16 v[28:31], v[156:159], v[172:175], v[28:31]
	v_mfma_f32_16x16x32_bf16 v[20:23], v[148:151], v[180:183], v[20:23]
	v_mfma_f32_16x16x32_bf16 v[12:15], v[156:159], v[180:183], v[12:15]
	v_mfma_f32_16x16x32_bf16 v[4:7], v[148:151], v[188:191], v[4:7]
	v_mfma_f32_16x16x32_bf16 v[0:3], v[156:159], v[188:191], v[0:3]
	s_barrier
	s_add_i32 s62, 0, 0x18000
	s_add_i32 s63, 0, 0x1c000
	v_add_u32_e32 v140, s62, v245
	v_add_u32_e32 v156, s63, v245
	ds_read_b128 v[128:131], v140
	ds_read_b128 v[132:135], v140 offset:1024
	ds_read_b128 v[136:139], v140 offset:2048
	ds_read_b128 v[140:143], v140 offset:3072
	ds_read_b128 v[144:147], v156
	ds_read_b128 v[148:151], v156 offset:1024
	ds_read_b128 v[152:155], v156 offset:2048
	ds_read_b128 v[156:159], v156 offset:3072
	s_add_u32 s34, s34, 0x40000
	s_addc_u32 s35, s35, 0
	s_mov_b32 m0, s38
	v_lshl_add_u64 v[200:201], s[34:35], 0, v[214:215]
	ds_read_b128 v[160:163], v248 offset:32768
	ds_read_b128 v[164:167], v248 offset:33792
	ds_read_b128 v[168:171], v248 offset:34816
	ds_read_b128 v[172:175], v248 offset:35840
	ds_read_b128 v[176:179], v248 offset:36864
	ds_read_b128 v[180:183], v248 offset:37888
	ds_read_b128 v[184:187], v248 offset:38912
	ds_read_b128 v[188:191], v248 offset:39936
	global_load_lds_dwordx4 v[200:201], off
	v_lshl_add_u64 v[200:201], s[34:35], 0, v[210:211]
	s_mov_b32 m0, s39
	s_nop 0
	global_load_lds_dwordx4 v[200:201], off
	s_waitcnt vmcnt(8) lgkmcnt(0)
	s_barrier
	v_mfma_f32_16x16x32_bf16 v[124:127], v[128:131], v[160:163], v[124:127]
	v_mfma_f32_16x16x32_bf16 v[120:123], v[136:139], v[160:163], v[120:123]
	v_mfma_f32_16x16x32_bf16 v[112:115], v[128:131], v[168:171], v[112:115]
	v_mfma_f32_16x16x32_bf16 v[104:107], v[136:139], v[168:171], v[104:107]
	v_mfma_f32_16x16x32_bf16 v[96:99], v[128:131], v[176:179], v[96:99]
	v_mfma_f32_16x16x32_bf16 v[88:91], v[136:139], v[176:179], v[88:91]
	v_mfma_f32_16x16x32_bf16 v[80:83], v[128:131], v[184:187], v[80:83]
	v_mfma_f32_16x16x32_bf16 v[72:75], v[136:139], v[184:187], v[72:75]
	v_mfma_f32_16x16x32_bf16 v[124:127], v[132:135], v[164:167], v[124:127]
	v_mfma_f32_16x16x32_bf16 v[120:123], v[140:143], v[164:167], v[120:123]
	v_mfma_f32_16x16x32_bf16 v[112:115], v[132:135], v[172:175], v[112:115]
	v_mfma_f32_16x16x32_bf16 v[104:107], v[140:143], v[172:175], v[104:107]
	v_mfma_f32_16x16x32_bf16 v[96:99], v[132:135], v[180:183], v[96:99]
	v_mfma_f32_16x16x32_bf16 v[88:91], v[140:143], v[180:183], v[88:91]
	v_mfma_f32_16x16x32_bf16 v[80:83], v[132:135], v[188:191], v[80:83]
	v_mfma_f32_16x16x32_bf16 v[72:75], v[140:143], v[188:191], v[72:75]
	v_mfma_f32_16x16x32_bf16 v[116:119], v[144:147], v[160:163], v[116:119]
	v_mfma_f32_16x16x32_bf16 v[108:111], v[152:155], v[160:163], v[108:111]
	v_mfma_f32_16x16x32_bf16 v[100:103], v[144:147], v[168:171], v[100:103]
	v_mfma_f32_16x16x32_bf16 v[92:95], v[152:155], v[168:171], v[92:95]
	v_mfma_f32_16x16x32_bf16 v[84:87], v[144:147], v[176:179], v[84:87]
	v_mfma_f32_16x16x32_bf16 v[76:79], v[152:155], v[176:179], v[76:79]
	v_mfma_f32_16x16x32_bf16 v[68:71], v[144:147], v[184:187], v[68:71]
	v_mfma_f32_16x16x32_bf16 v[64:67], v[152:155], v[184:187], v[64:67]
	v_mfma_f32_16x16x32_bf16 v[116:119], v[148:151], v[164:167], v[116:119]
	v_mfma_f32_16x16x32_bf16 v[108:111], v[156:159], v[164:167], v[108:111]
	v_mfma_f32_16x16x32_bf16 v[100:103], v[148:151], v[172:175], v[100:103]
	v_mfma_f32_16x16x32_bf16 v[92:95], v[156:159], v[172:175], v[92:95]
	v_mfma_f32_16x16x32_bf16 v[84:87], v[148:151], v[180:183], v[84:87]
	v_mfma_f32_16x16x32_bf16 v[76:79], v[156:159], v[180:183], v[76:79]
	v_mfma_f32_16x16x32_bf16 v[68:71], v[148:151], v[188:191], v[68:71]
	v_mfma_f32_16x16x32_bf16 v[64:67], v[156:159], v[188:191], v[64:67]
	s_barrier
	s_add_i32 s34, s62, s3
	v_lshl_add_u64 v[192:193], v[192:193], 0, s[10:11]
	s_mov_b32 m0, s34
	ds_read_b128 v[160:163], v248 offset:49152
	ds_read_b128 v[164:167], v248 offset:50176
	ds_read_b128 v[168:171], v248 offset:51200
	ds_read_b128 v[172:175], v248 offset:52224
	ds_read_b128 v[176:179], v248 offset:53248
	ds_read_b128 v[180:183], v248 offset:54272
	ds_read_b128 v[184:187], v248 offset:55296
	ds_read_b128 v[188:191], v248 offset:56320
	global_load_lds_dwordx4 v[192:193], off
	s_add_i32 m0, s34, 0x2000
	s_add_u32 s6, s6, 0x40080
	v_lshl_add_u64 v[192:193], v[194:195], 0, s[10:11]
	s_addc_u32 s7, s7, 0
	s_add_i32 s34, s63, s3
	global_load_lds_dwordx4 v[192:193], off
	v_lshl_add_u64 v[192:193], s[6:7], 0, v[212:213]
	s_mov_b32 m0, s34
	s_nop 0
	global_load_lds_dwordx4 v[192:193], off
	v_lshl_add_u64 v[192:193], s[6:7], 0, v[208:209]
	s_add_i32 m0, s34, 0x2000
	s_nop 0
	global_load_lds_dwordx4 v[192:193], off
	v_lshl_add_u64 v[192:193], v[196:197], 0, s[10:11]
	s_mov_b32 m0, s44
	s_nop 0
	global_load_lds_dwordx4 v[192:193], off
	v_lshl_add_u64 v[192:193], v[198:199], 0, s[10:11]
	s_mov_b32 m0, s45
	s_nop 0
	global_load_lds_dwordx4 v[192:193], off
	s_waitcnt vmcnt(8) lgkmcnt(0)
	s_barrier
	v_mfma_f32_16x16x32_bf16 v[60:63], v[128:131], v[160:163], v[60:63]
	v_mfma_f32_16x16x32_bf16 v[56:59], v[136:139], v[160:163], v[56:59]
	v_mfma_f32_16x16x32_bf16 v[48:51], v[128:131], v[168:171], v[48:51]
	v_mfma_f32_16x16x32_bf16 v[40:43], v[136:139], v[168:171], v[40:43]
	v_mfma_f32_16x16x32_bf16 v[32:35], v[128:131], v[176:179], v[32:35]
	v_mfma_f32_16x16x32_bf16 v[24:27], v[136:139], v[176:179], v[24:27]
	v_mfma_f32_16x16x32_bf16 v[16:19], v[128:131], v[184:187], v[16:19]
	v_mfma_f32_16x16x32_bf16 v[8:11], v[136:139], v[184:187], v[8:11]
	v_mfma_f32_16x16x32_bf16 v[60:63], v[132:135], v[164:167], v[60:63]
	v_mfma_f32_16x16x32_bf16 v[56:59], v[140:143], v[164:167], v[56:59]
	v_mfma_f32_16x16x32_bf16 v[48:51], v[132:135], v[172:175], v[48:51]
	v_mfma_f32_16x16x32_bf16 v[40:43], v[140:143], v[172:175], v[40:43]
	v_mfma_f32_16x16x32_bf16 v[32:35], v[132:135], v[180:183], v[32:35]
	v_mfma_f32_16x16x32_bf16 v[24:27], v[140:143], v[180:183], v[24:27]
	v_mfma_f32_16x16x32_bf16 v[16:19], v[132:135], v[188:191], v[16:19]
	v_mfma_f32_16x16x32_bf16 v[8:11], v[140:143], v[188:191], v[8:11]
	v_mfma_f32_16x16x32_bf16 v[52:55], v[144:147], v[160:163], v[52:55]
	v_mfma_f32_16x16x32_bf16 v[44:47], v[152:155], v[160:163], v[44:47]
	v_mfma_f32_16x16x32_bf16 v[36:39], v[144:147], v[168:171], v[36:39]
	v_mfma_f32_16x16x32_bf16 v[28:31], v[152:155], v[168:171], v[28:31]
	v_mfma_f32_16x16x32_bf16 v[20:23], v[144:147], v[176:179], v[20:23]
	v_mfma_f32_16x16x32_bf16 v[12:15], v[152:155], v[176:179], v[12:15]
	v_mfma_f32_16x16x32_bf16 v[4:7], v[144:147], v[184:187], v[4:7]
	v_mfma_f32_16x16x32_bf16 v[0:3], v[152:155], v[184:187], v[0:3]
	v_mfma_f32_16x16x32_bf16 v[52:55], v[148:151], v[164:167], v[52:55]
	v_mfma_f32_16x16x32_bf16 v[44:47], v[156:159], v[164:167], v[44:47]
	v_mfma_f32_16x16x32_bf16 v[36:39], v[148:151], v[172:175], v[36:39]
	v_mfma_f32_16x16x32_bf16 v[28:31], v[156:159], v[172:175], v[28:31]
	v_mfma_f32_16x16x32_bf16 v[20:23], v[148:151], v[180:183], v[20:23]
	v_mfma_f32_16x16x32_bf16 v[12:15], v[156:159], v[180:183], v[12:15]
	v_mfma_f32_16x16x32_bf16 v[4:7], v[148:151], v[188:191], v[4:7]
	v_mfma_f32_16x16x32_bf16 v[0:3], v[156:159], v[188:191], v[0:3]
	s_barrier
	s_add_i32 s61, s61, 2
	s_add_u32 s23, s23, 0x100
	s_addc_u32 s60, s60, 0
	s_add_u32 s4, s4, 0x100
	s_addc_u32 s5, s5, 0
	s_cmp_gt_u32 s61, 13
	s_cbranch_scc0 .LBB0_1519
	s_and_b64 vcc, exec, s[12:13]
	s_cbranch_vccz .LBB0_1522
	s_barrier
